# top-k threshold search rewritten as bit-sliced radix select: keys bit-transposed in registers (32 per plane word), and+popcount per round instead of compare+add per key, selection mask taken from the
# speedup vs baseline: 1.0219x; 1.0157x over previous
; DI void a1_task(unsigned char* shm, const bf16_t* prm, const bf16_t* prt, unsigned* mask, int b, int qt, const int tid) {
;     ...
;     unsigned T = 0u;
;     if (qt >= 8) {
;         const int nheld = (qt >= wid) ? ((qt - wid) >> 3) + 1 : 0;
;         bool done = false;
;     ...
;             const unsigned cand = T | (1u << bit);
;             int c = 0;
; #pragma unroll
;             for (int jt = 0; jt < 8; ++jt) {
;                 if (jt < nheld) {
; #pragma unroll
;                     for (int i = 0; i < 16; ++i) c += (key[jt][i] >= cand) ? 1 : 0;
;                 }
;             }
.LBB0_458:
	s_cmp_lt_i32 s2, 8
	v_mov_b32_e32 v0, 1
	s_cbranch_scc1 .LBB0_480
	v_readlane_b32 s0, v255, 40
	s_mov_b64 s[8:9], exec
	s_sub_i32 s41, s2, s0
	s_mov_b32 s42, 0x5040100
	s_mov_b32 s43, 0x7060302
	s_mov_b32 s44, 0x6020400
	s_mov_b32 s45, 0x7030501
	s_mov_b32 s46, 0x0f0f0f0f
	s_mov_b32 s47, 0x33333333
	s_mov_b32 s48, 0x55555555
	v_perm_b32 v18, v166, v142, s42
	v_perm_b32 v166, v166, v142, s43
	v_perm_b32 v142, v167, v141, s42
	v_perm_b32 v167, v167, v141, s43
	v_perm_b32 v141, v159, v144, s42
	v_perm_b32 v159, v159, v144, s43
	v_perm_b32 v144, v158, v143, s42
	v_perm_b32 v158, v158, v143, s43
	v_perm_b32 v143, v161, v146, s42
	v_perm_b32 v161, v161, v146, s43
	v_perm_b32 v146, v160, v145, s42
	v_perm_b32 v160, v160, v145, s43
	v_perm_b32 v145, v163, v149, s42
	v_perm_b32 v163, v163, v149, s43
	v_perm_b32 v149, v162, v147, s42
	v_perm_b32 v162, v162, v147, s43
	v_perm_b32 v147, v165, v151, s42
	v_perm_b32 v165, v165, v151, s43
	v_perm_b32 v151, v164, v150, s42
	v_perm_b32 v164, v164, v150, s43
	v_perm_b32 v150, v169, v153, s42
	v_perm_b32 v169, v169, v153, s43
	v_perm_b32 v153, v168, v152, s42
	v_perm_b32 v168, v168, v152, s43
	v_perm_b32 v152, v171, v155, s42
	v_perm_b32 v171, v171, v155, s43
	v_perm_b32 v155, v170, v154, s42
	v_perm_b32 v170, v170, v154, s43
	v_perm_b32 v154, v173, v157, s42
	v_perm_b32 v173, v173, v157, s43
	v_perm_b32 v157, v172, v156, s42
	v_perm_b32 v172, v172, v156, s43
	v_perm_b32 v156, v147, v18, s44
	v_perm_b32 v147, v147, v18, s45
	v_perm_b32 v18, v151, v142, s44
	v_perm_b32 v151, v151, v142, s45
	v_perm_b32 v142, v150, v141, s44
	v_perm_b32 v150, v150, v141, s45
	v_perm_b32 v141, v153, v144, s44
	v_perm_b32 v153, v153, v144, s45
	v_perm_b32 v144, v152, v143, s44
	v_perm_b32 v152, v152, v143, s45
	v_perm_b32 v143, v155, v146, s44
	v_perm_b32 v155, v155, v146, s45
	v_perm_b32 v146, v154, v145, s44
	v_perm_b32 v154, v154, v145, s45
	v_perm_b32 v145, v157, v149, s44
	v_perm_b32 v157, v157, v149, s45
	v_perm_b32 v149, v165, v166, s44
	v_perm_b32 v165, v165, v166, s45
	v_perm_b32 v166, v164, v167, s44
	v_perm_b32 v164, v164, v167, s45
	v_perm_b32 v167, v169, v159, s44
	v_perm_b32 v169, v169, v159, s45
	v_perm_b32 v159, v168, v158, s44
	v_perm_b32 v168, v168, v158, s45
	v_perm_b32 v158, v171, v161, s44
	v_perm_b32 v171, v171, v161, s45
	v_perm_b32 v161, v170, v160, s44
	v_perm_b32 v170, v170, v160, s45
	v_perm_b32 v160, v173, v163, s44
	v_perm_b32 v173, v173, v163, s45
	v_perm_b32 v163, v172, v162, s44
	v_perm_b32 v172, v172, v162, s45
	v_lshlrev_b32_e32 v22, 4, v144
	v_lshrrev_b32_e32 v23, 4, v156
	v_bfi_b32 v156, s46, v156, v22
	v_bfi_b32 v144, s46, v23, v144
	v_lshlrev_b32_e32 v22, 4, v143
	v_lshrrev_b32_e32 v23, 4, v18
	v_bfi_b32 v18, s46, v18, v22
	v_bfi_b32 v143, s46, v23, v143
	v_lshlrev_b32_e32 v22, 4, v146
	v_lshrrev_b32_e32 v23, 4, v142
	v_bfi_b32 v142, s46, v142, v22
	v_bfi_b32 v146, s46, v23, v146
	v_lshlrev_b32_e32 v22, 4, v145
	v_lshrrev_b32_e32 v23, 4, v141
	v_bfi_b32 v141, s46, v141, v22
	v_bfi_b32 v145, s46, v23, v145
	v_lshlrev_b32_e32 v22, 4, v152
	v_lshrrev_b32_e32 v23, 4, v147
	v_bfi_b32 v147, s46, v147, v22
	v_bfi_b32 v152, s46, v23, v152
	v_lshlrev_b32_e32 v22, 4, v155
	v_lshrrev_b32_e32 v23, 4, v151
	v_bfi_b32 v151, s46, v151, v22
	v_bfi_b32 v155, s46, v23, v155
	v_lshlrev_b32_e32 v22, 4, v154
	v_lshrrev_b32_e32 v23, 4, v150
	v_bfi_b32 v150, s46, v150, v22
	v_bfi_b32 v154, s46, v23, v154
	v_lshlrev_b32_e32 v22, 4, v157
	v_lshrrev_b32_e32 v23, 4, v153
	v_bfi_b32 v153, s46, v153, v22
	v_bfi_b32 v157, s46, v23, v157
	v_lshlrev_b32_e32 v22, 4, v158
	v_lshrrev_b32_e32 v23, 4, v149
	v_bfi_b32 v149, s46, v149, v22
	v_bfi_b32 v158, s46, v23, v158
	v_lshlrev_b32_e32 v22, 4, v161
	v_lshrrev_b32_e32 v23, 4, v166
	v_bfi_b32 v166, s46, v166, v22
	v_bfi_b32 v161, s46, v23, v161
	v_lshlrev_b32_e32 v22, 4, v160
	v_lshrrev_b32_e32 v23, 4, v167
	v_bfi_b32 v167, s46, v167, v22
	v_bfi_b32 v160, s46, v23, v160
	v_lshlrev_b32_e32 v22, 4, v163
	v_lshrrev_b32_e32 v23, 4, v159
	v_bfi_b32 v159, s46, v159, v22
	v_bfi_b32 v163, s46, v23, v163
	v_lshlrev_b32_e32 v22, 4, v171
	v_lshrrev_b32_e32 v23, 4, v165
	v_bfi_b32 v165, s46, v165, v22
	v_bfi_b32 v171, s46, v23, v171
	v_lshlrev_b32_e32 v22, 4, v170
	v_lshrrev_b32_e32 v23, 4, v164
	v_bfi_b32 v164, s46, v164, v22
	v_bfi_b32 v170, s46, v23, v170
	v_lshlrev_b32_e32 v22, 4, v173
	v_lshrrev_b32_e32 v23, 4, v169
	v_bfi_b32 v169, s46, v169, v22
	v_bfi_b32 v173, s46, v23, v173
	v_lshlrev_b32_e32 v22, 4, v172
	v_lshrrev_b32_e32 v23, 4, v168
	v_bfi_b32 v168, s46, v168, v22
	v_bfi_b32 v172, s46, v23, v172
	v_lshlrev_b32_e32 v22, 2, v142
	v_lshrrev_b32_e32 v23, 2, v156
	v_bfi_b32 v156, s47, v156, v22
	v_bfi_b32 v142, s47, v23, v142
	v_lshlrev_b32_e32 v22, 2, v141
	v_lshrrev_b32_e32 v23, 2, v18
	v_bfi_b32 v18, s47, v18, v22
	v_bfi_b32 v141, s47, v23, v141
	v_lshlrev_b32_e32 v22, 2, v146
	v_lshrrev_b32_e32 v23, 2, v144
	v_bfi_b32 v144, s47, v144, v22
	v_bfi_b32 v146, s47, v23, v146
	v_lshlrev_b32_e32 v22, 2, v145
	v_lshrrev_b32_e32 v23, 2, v143
	v_bfi_b32 v143, s47, v143, v22
	v_bfi_b32 v145, s47, v23, v145
	v_lshlrev_b32_e32 v22, 2, v150
	v_lshrrev_b32_e32 v23, 2, v147
	v_bfi_b32 v147, s47, v147, v22
	v_bfi_b32 v150, s47, v23, v150
	v_lshlrev_b32_e32 v22, 2, v153
	v_lshrrev_b32_e32 v23, 2, v151
	v_bfi_b32 v151, s47, v151, v22
	v_bfi_b32 v153, s47, v23, v153
	v_lshlrev_b32_e32 v22, 2, v154
	v_lshrrev_b32_e32 v23, 2, v152
	v_bfi_b32 v152, s47, v152, v22
	v_bfi_b32 v154, s47, v23, v154
	v_lshlrev_b32_e32 v22, 2, v157
	v_lshrrev_b32_e32 v23, 2, v155
	v_bfi_b32 v155, s47, v155, v22
	v_bfi_b32 v157, s47, v23, v157
	v_lshlrev_b32_e32 v22, 2, v167
	v_lshrrev_b32_e32 v23, 2, v149
; DI void a1_task(unsigned char* shm, const bf16_t* prm, const bf16_t* prt, unsigned* mask, int b, int qt, const int tid) {
;     ...
;     unsigned T = 0u;
;     if (qt >= 8) {
;         const int nheld = (qt >= wid) ? ((qt - wid) >> 3) + 1 : 0;
;         bool done = false;
;     ...
;             const unsigned cand = T | (1u << bit);
;             int c = 0;
; #pragma unroll
;             for (int jt = 0; jt < 8; ++jt) {
;                 if (jt < nheld) {
; #pragma unroll
;                     for (int i = 0; i < 16; ++i) c += (key[jt][i] >= cand) ? 1 : 0;
;                 }
;             }
	v_bfi_b32 v149, s47, v149, v22
	v_bfi_b32 v167, s47, v23, v167
	v_lshlrev_b32_e32 v22, 2, v159
	v_lshrrev_b32_e32 v23, 2, v166
	v_bfi_b32 v166, s47, v166, v22
	v_bfi_b32 v159, s47, v23, v159
	v_lshlrev_b32_e32 v22, 2, v160
	v_lshrrev_b32_e32 v23, 2, v158
	v_bfi_b32 v158, s47, v158, v22
	v_bfi_b32 v160, s47, v23, v160
	v_lshlrev_b32_e32 v22, 2, v163
	v_lshrrev_b32_e32 v23, 2, v161
	v_bfi_b32 v161, s47, v161, v22
	v_bfi_b32 v163, s47, v23, v163
	v_lshlrev_b32_e32 v22, 2, v169
	v_lshrrev_b32_e32 v23, 2, v165
	v_bfi_b32 v165, s47, v165, v22
	v_bfi_b32 v169, s47, v23, v169
	v_lshlrev_b32_e32 v22, 2, v168
	v_lshrrev_b32_e32 v23, 2, v164
	v_bfi_b32 v164, s47, v164, v22
	v_bfi_b32 v168, s47, v23, v168
	v_lshlrev_b32_e32 v22, 2, v173
	v_lshrrev_b32_e32 v23, 2, v171
	v_bfi_b32 v171, s47, v171, v22
	v_bfi_b32 v173, s47, v23, v173
	v_lshlrev_b32_e32 v22, 2, v172
	v_lshrrev_b32_e32 v23, 2, v170
	v_bfi_b32 v170, s47, v170, v22
	v_bfi_b32 v172, s47, v23, v172
	v_lshlrev_b32_e32 v22, 1, v18
	v_lshrrev_b32_e32 v23, 1, v156
	v_bfi_b32 v156, s48, v156, v22
	v_bfi_b32 v18, s48, v23, v18
	v_lshlrev_b32_e32 v22, 1, v141
	v_lshrrev_b32_e32 v23, 1, v142
	v_bfi_b32 v142, s48, v142, v22
	v_bfi_b32 v141, s48, v23, v141
	v_lshlrev_b32_e32 v22, 1, v143
	v_lshrrev_b32_e32 v23, 1, v144
	v_bfi_b32 v144, s48, v144, v22
	v_bfi_b32 v143, s48, v23, v143
	v_lshlrev_b32_e32 v22, 1, v145
	v_lshrrev_b32_e32 v23, 1, v146
	v_bfi_b32 v146, s48, v146, v22
	v_bfi_b32 v145, s48, v23, v145
	v_lshlrev_b32_e32 v22, 1, v151
	v_lshrrev_b32_e32 v23, 1, v147
	v_bfi_b32 v147, s48, v147, v22
	v_bfi_b32 v151, s48, v23, v151
	v_lshlrev_b32_e32 v22, 1, v153
	v_lshrrev_b32_e32 v23, 1, v150
	v_bfi_b32 v150, s48, v150, v22
	v_bfi_b32 v153, s48, v23, v153
	v_lshlrev_b32_e32 v22, 1, v155
	v_lshrrev_b32_e32 v23, 1, v152
	v_bfi_b32 v152, s48, v152, v22
	v_bfi_b32 v155, s48, v23, v155
	v_lshlrev_b32_e32 v22, 1, v157
	v_lshrrev_b32_e32 v23, 1, v154
	v_bfi_b32 v154, s48, v154, v22
	v_bfi_b32 v157, s48, v23, v157
	v_lshlrev_b32_e32 v22, 1, v166
	v_lshrrev_b32_e32 v23, 1, v149
	v_bfi_b32 v149, s48, v149, v22
	v_bfi_b32 v166, s48, v23, v166
	v_lshlrev_b32_e32 v22, 1, v159
	v_lshrrev_b32_e32 v23, 1, v167
	v_bfi_b32 v167, s48, v167, v22
	v_bfi_b32 v159, s48, v23, v159
	v_lshlrev_b32_e32 v22, 1, v161
	v_lshrrev_b32_e32 v23, 1, v158
	v_bfi_b32 v158, s48, v158, v22
	v_bfi_b32 v161, s48, v23, v161
	v_lshlrev_b32_e32 v22, 1, v163
	v_lshrrev_b32_e32 v23, 1, v160
	v_bfi_b32 v160, s48, v160, v22
	v_bfi_b32 v163, s48, v23, v163
	v_lshlrev_b32_e32 v22, 1, v164
	v_lshrrev_b32_e32 v23, 1, v165
	v_bfi_b32 v165, s48, v165, v22
	v_bfi_b32 v164, s48, v23, v164
	v_lshlrev_b32_e32 v22, 1, v168
	v_lshrrev_b32_e32 v23, 1, v169
	v_bfi_b32 v169, s48, v169, v22
	v_bfi_b32 v168, s48, v23, v168
	v_lshlrev_b32_e32 v22, 1, v170
	v_lshrrev_b32_e32 v23, 1, v171
	v_bfi_b32 v171, s48, v171, v22
	v_bfi_b32 v170, s48, v23, v170
	v_lshlrev_b32_e32 v22, 1, v172
	v_lshrrev_b32_e32 v23, 1, v173
	v_bfi_b32 v173, s48, v173, v22
	v_bfi_b32 v172, s48, v23, v172
	s_cmp_lt_i32 s41, 16
	s_cbranch_scc1 .Lbs_tr_done
	v_perm_b32 v19, v191, v175, s42
	v_perm_b32 v191, v191, v175, s43
	v_perm_b32 v175, v190, v174, s42
	v_perm_b32 v190, v190, v174, s43
	v_perm_b32 v174, v193, v177, s42
	v_perm_b32 v193, v193, v177, s43
	v_perm_b32 v177, v192, v176, s42
	v_perm_b32 v192, v192, v176, s43
	v_perm_b32 v176, v212, v179, s42
	v_perm_b32 v212, v212, v179, s43
	v_perm_b32 v179, v211, v178, s42
	v_perm_b32 v211, v211, v178, s43
	v_perm_b32 v178, v214, v181, s42
	v_perm_b32 v214, v214, v181, s43
	v_perm_b32 v181, v213, v180, s42
	v_perm_b32 v213, v213, v180, s43
	v_perm_b32 v180, v216, v183, s42
	v_perm_b32 v216, v216, v183, s43
	v_perm_b32 v183, v215, v182, s42
	v_perm_b32 v215, v215, v182, s43
	v_perm_b32 v182, v218, v185, s42
	v_perm_b32 v218, v218, v185, s43
	v_perm_b32 v185, v217, v184, s42
	v_perm_b32 v217, v217, v184, s43
	v_perm_b32 v184, v220, v187, s42
	v_perm_b32 v220, v220, v187, s43
	v_perm_b32 v187, v219, v186, s42
	v_perm_b32 v219, v219, v186, s43
	v_perm_b32 v186, v222, v189, s42
	v_perm_b32 v222, v222, v189, s43
	v_perm_b32 v189, v221, v188, s42
	v_perm_b32 v221, v221, v188, s43
	v_perm_b32 v188, v180, v19, s44
	v_perm_b32 v180, v180, v19, s45
	v_perm_b32 v19, v183, v175, s44
	v_perm_b32 v183, v183, v175, s45
	v_perm_b32 v175, v182, v174, s44
	v_perm_b32 v182, v182, v174, s45
	v_perm_b32 v174, v185, v177, s44
	v_perm_b32 v185, v185, v177, s45
	v_perm_b32 v177, v184, v176, s44
	v_perm_b32 v184, v184, v176, s45
	v_perm_b32 v176, v187, v179, s44
	v_perm_b32 v187, v187, v179, s45
	v_perm_b32 v179, v186, v178, s44
	v_perm_b32 v186, v186, v178, s45
	v_perm_b32 v178, v189, v181, s44
	v_perm_b32 v189, v189, v181, s45
	v_perm_b32 v181, v216, v191, s44
	v_perm_b32 v216, v216, v191, s45
	v_perm_b32 v191, v215, v190, s44
	v_perm_b32 v215, v215, v190, s45
	v_perm_b32 v190, v218, v193, s44
	v_perm_b32 v218, v218, v193, s45
	v_perm_b32 v193, v217, v192, s44
	v_perm_b32 v217, v217, v192, s45
	v_perm_b32 v192, v220, v212, s44
	v_perm_b32 v220, v220, v212, s45
	v_perm_b32 v212, v219, v211, s44
	v_perm_b32 v219, v219, v211, s45
	v_perm_b32 v211, v222, v214, s44
	v_perm_b32 v222, v222, v214, s45
	v_perm_b32 v214, v221, v213, s44
	v_perm_b32 v221, v221, v213, s45
	v_lshlrev_b32_e32 v22, 4, v177
	v_lshrrev_b32_e32 v23, 4, v188
	v_bfi_b32 v188, s46, v188, v22
	v_bfi_b32 v177, s46, v23, v177
	v_lshlrev_b32_e32 v22, 4, v176
	v_lshrrev_b32_e32 v23, 4, v19
	v_bfi_b32 v19, s46, v19, v22
	v_bfi_b32 v176, s46, v23, v176
	v_lshlrev_b32_e32 v22, 4, v179
	v_lshrrev_b32_e32 v23, 4, v175
	v_bfi_b32 v175, s46, v175, v22
	v_bfi_b32 v179, s46, v23, v179
	v_lshlrev_b32_e32 v22, 4, v178
; DI void a1_task(unsigned char* shm, const bf16_t* prm, const bf16_t* prt, unsigned* mask, int b, int qt, const int tid) {
;     ...
;     if (qt >= 8) {
;         const int nheld = (qt >= wid) ? ((qt - wid) >> 3) + 1 : 0;
;         bool done = false;
;     ...
;             const unsigned cand = T | (1u << bit);
;             int c = 0;
; #pragma unroll
;             for (int jt = 0; jt < 8; ++jt) {
;                 if (jt < nheld) {
; #pragma unroll
;                     for (int i = 0; i < 16; ++i) c += (key[jt][i] >= cand) ? 1 : 0;
;                 }
;             }
	v_lshrrev_b32_e32 v23, 4, v174
	v_bfi_b32 v174, s46, v174, v22
	v_bfi_b32 v178, s46, v23, v178
	v_lshlrev_b32_e32 v22, 4, v184
	v_lshrrev_b32_e32 v23, 4, v180
	v_bfi_b32 v180, s46, v180, v22
	v_bfi_b32 v184, s46, v23, v184
	v_lshlrev_b32_e32 v22, 4, v187
	v_lshrrev_b32_e32 v23, 4, v183
	v_bfi_b32 v183, s46, v183, v22
	v_bfi_b32 v187, s46, v23, v187
	v_lshlrev_b32_e32 v22, 4, v186
	v_lshrrev_b32_e32 v23, 4, v182
	v_bfi_b32 v182, s46, v182, v22
	v_bfi_b32 v186, s46, v23, v186
	v_lshlrev_b32_e32 v22, 4, v189
	v_lshrrev_b32_e32 v23, 4, v185
	v_bfi_b32 v185, s46, v185, v22
	v_bfi_b32 v189, s46, v23, v189
	v_lshlrev_b32_e32 v22, 4, v192
	v_lshrrev_b32_e32 v23, 4, v181
	v_bfi_b32 v181, s46, v181, v22
	v_bfi_b32 v192, s46, v23, v192
	v_lshlrev_b32_e32 v22, 4, v212
	v_lshrrev_b32_e32 v23, 4, v191
	v_bfi_b32 v191, s46, v191, v22
	v_bfi_b32 v212, s46, v23, v212
	v_lshlrev_b32_e32 v22, 4, v211
	v_lshrrev_b32_e32 v23, 4, v190
	v_bfi_b32 v190, s46, v190, v22
	v_bfi_b32 v211, s46, v23, v211
	v_lshlrev_b32_e32 v22, 4, v214
	v_lshrrev_b32_e32 v23, 4, v193
	v_bfi_b32 v193, s46, v193, v22
	v_bfi_b32 v214, s46, v23, v214
	v_lshlrev_b32_e32 v22, 4, v220
	v_lshrrev_b32_e32 v23, 4, v216
	v_bfi_b32 v216, s46, v216, v22
	v_bfi_b32 v220, s46, v23, v220
	v_lshlrev_b32_e32 v22, 4, v219
	v_lshrrev_b32_e32 v23, 4, v215
	v_bfi_b32 v215, s46, v215, v22
	v_bfi_b32 v219, s46, v23, v219
	v_lshlrev_b32_e32 v22, 4, v222
	v_lshrrev_b32_e32 v23, 4, v218
	v_bfi_b32 v218, s46, v218, v22
	v_bfi_b32 v222, s46, v23, v222
	v_lshlrev_b32_e32 v22, 4, v221
	v_lshrrev_b32_e32 v23, 4, v217
	v_bfi_b32 v217, s46, v217, v22
	v_bfi_b32 v221, s46, v23, v221
	v_lshlrev_b32_e32 v22, 2, v175
	v_lshrrev_b32_e32 v23, 2, v188
	v_bfi_b32 v188, s47, v188, v22
	v_bfi_b32 v175, s47, v23, v175
	v_lshlrev_b32_e32 v22, 2, v174
	v_lshrrev_b32_e32 v23, 2, v19
	v_bfi_b32 v19, s47, v19, v22
	v_bfi_b32 v174, s47, v23, v174
	v_lshlrev_b32_e32 v22, 2, v179
	v_lshrrev_b32_e32 v23, 2, v177
	v_bfi_b32 v177, s47, v177, v22
	v_bfi_b32 v179, s47, v23, v179
	v_lshlrev_b32_e32 v22, 2, v178
	v_lshrrev_b32_e32 v23, 2, v176
	v_bfi_b32 v176, s47, v176, v22
	v_bfi_b32 v178, s47, v23, v178
	v_lshlrev_b32_e32 v22, 2, v182
	v_lshrrev_b32_e32 v23, 2, v180
	v_bfi_b32 v180, s47, v180, v22
	v_bfi_b32 v182, s47, v23, v182
	v_lshlrev_b32_e32 v22, 2, v185
	v_lshrrev_b32_e32 v23, 2, v183
	v_bfi_b32 v183, s47, v183, v22
	v_bfi_b32 v185, s47, v23, v185
	v_lshlrev_b32_e32 v22, 2, v186
	v_lshrrev_b32_e32 v23, 2, v184
	v_bfi_b32 v184, s47, v184, v22
	v_bfi_b32 v186, s47, v23, v186
	v_lshlrev_b32_e32 v22, 2, v189
	v_lshrrev_b32_e32 v23, 2, v187
	v_bfi_b32 v187, s47, v187, v22
	v_bfi_b32 v189, s47, v23, v189
	v_lshlrev_b32_e32 v22, 2, v190
	v_lshrrev_b32_e32 v23, 2, v181
	v_bfi_b32 v181, s47, v181, v22
	v_bfi_b32 v190, s47, v23, v190
	v_lshlrev_b32_e32 v22, 2, v193
	v_lshrrev_b32_e32 v23, 2, v191
	v_bfi_b32 v191, s47, v191, v22
	v_bfi_b32 v193, s47, v23, v193
	v_lshlrev_b32_e32 v22, 2, v211
	v_lshrrev_b32_e32 v23, 2, v192
	v_bfi_b32 v192, s47, v192, v22
	v_bfi_b32 v211, s47, v23, v211
	v_lshlrev_b32_e32 v22, 2, v214
	v_lshrrev_b32_e32 v23, 2, v212
	v_bfi_b32 v212, s47, v212, v22
	v_bfi_b32 v214, s47, v23, v214
	v_lshlrev_b32_e32 v22, 2, v218
	v_lshrrev_b32_e32 v23, 2, v216
	v_bfi_b32 v216, s47, v216, v22
	v_bfi_b32 v218, s47, v23, v218
	v_lshlrev_b32_e32 v22, 2, v217
	v_lshrrev_b32_e32 v23, 2, v215
	v_bfi_b32 v215, s47, v215, v22
	v_bfi_b32 v217, s47, v23, v217
	v_lshlrev_b32_e32 v22, 2, v222
	v_lshrrev_b32_e32 v23, 2, v220
	v_bfi_b32 v220, s47, v220, v22
	v_bfi_b32 v222, s47, v23, v222
	v_lshlrev_b32_e32 v22, 2, v221
	v_lshrrev_b32_e32 v23, 2, v219
	v_bfi_b32 v219, s47, v219, v22
	v_bfi_b32 v221, s47, v23, v221
	v_lshlrev_b32_e32 v22, 1, v19
	v_lshrrev_b32_e32 v23, 1, v188
	v_bfi_b32 v188, s48, v188, v22
	v_bfi_b32 v19, s48, v23, v19
	v_lshlrev_b32_e32 v22, 1, v174
	v_lshrrev_b32_e32 v23, 1, v175
	v_bfi_b32 v175, s48, v175, v22
	v_bfi_b32 v174, s48, v23, v174
	v_lshlrev_b32_e32 v22, 1, v176
	v_lshrrev_b32_e32 v23, 1, v177
	v_bfi_b32 v177, s48, v177, v22
	v_bfi_b32 v176, s48, v23, v176
	v_lshlrev_b32_e32 v22, 1, v178
	v_lshrrev_b32_e32 v23, 1, v179
	v_bfi_b32 v179, s48, v179, v22
	v_bfi_b32 v178, s48, v23, v178
	v_lshlrev_b32_e32 v22, 1, v183
	v_lshrrev_b32_e32 v23, 1, v180
	v_bfi_b32 v180, s48, v180, v22
	v_bfi_b32 v183, s48, v23, v183
	v_lshlrev_b32_e32 v22, 1, v185
	v_lshrrev_b32_e32 v23, 1, v182
	v_bfi_b32 v182, s48, v182, v22
	v_bfi_b32 v185, s48, v23, v185
	v_lshlrev_b32_e32 v22, 1, v187
	v_lshrrev_b32_e32 v23, 1, v184
	v_bfi_b32 v184, s48, v184, v22
	v_bfi_b32 v187, s48, v23, v187
	v_lshlrev_b32_e32 v22, 1, v189
	v_lshrrev_b32_e32 v23, 1, v186
	v_bfi_b32 v186, s48, v186, v22
	v_bfi_b32 v189, s48, v23, v189
	v_lshlrev_b32_e32 v22, 1, v191
	v_lshrrev_b32_e32 v23, 1, v181
	v_bfi_b32 v181, s48, v181, v22
	v_bfi_b32 v191, s48, v23, v191
	v_lshlrev_b32_e32 v22, 1, v193
	v_lshrrev_b32_e32 v23, 1, v190
	v_bfi_b32 v190, s48, v190, v22
	v_bfi_b32 v193, s48, v23, v193
	v_lshlrev_b32_e32 v22, 1, v212
	v_lshrrev_b32_e32 v23, 1, v192
	v_bfi_b32 v192, s48, v192, v22
	v_bfi_b32 v212, s48, v23, v212
	v_lshlrev_b32_e32 v22, 1, v214
	v_lshrrev_b32_e32 v23, 1, v211
	v_bfi_b32 v211, s48, v211, v22
	v_bfi_b32 v214, s48, v23, v214
	v_lshlrev_b32_e32 v22, 1, v215
	v_lshrrev_b32_e32 v23, 1, v216
	v_bfi_b32 v216, s48, v216, v22
	v_bfi_b32 v215, s48, v23, v215
	v_lshlrev_b32_e32 v22, 1, v217
	v_lshrrev_b32_e32 v23, 1, v218
	v_bfi_b32 v218, s48, v218, v22
	v_bfi_b32 v217, s48, v23, v217
	v_lshlrev_b32_e32 v22, 1, v219
	v_lshrrev_b32_e32 v23, 1, v220
	v_bfi_b32 v220, s48, v220, v22
	v_bfi_b32 v219, s48, v23, v219
	v_lshlrev_b32_e32 v22, 1, v221
	v_lshrrev_b32_e32 v23, 1, v222
	v_bfi_b32 v222, s48, v222, v22
	v_bfi_b32 v221, s48, v23, v221
	s_cmp_lt_i32 s41, 32
	s_cbranch_scc1 .Lbs_tr_done
; DI void a1_task(unsigned char* shm, const bf16_t* prm, const bf16_t* prt, unsigned* mask, int b, int qt, const int tid) {
;     ...
;     if (qt >= 8) {
;         const int nheld = (qt >= wid) ? ((qt - wid) >> 3) + 1 : 0;
;         bool done = false;
;     ...
;             const unsigned cand = T | (1u << bit);
;             int c = 0;
; #pragma unroll
;             for (int jt = 0; jt < 8; ++jt) {
;                 if (jt < nheld) {
; #pragma unroll
;                     for (int i = 0; i < 16; ++i) c += (key[jt][i] >= cand) ? 1 : 0;
;                 }
;             }
	v_perm_b32 v20, v87, v83, s42
	v_perm_b32 v87, v87, v83, s43
	v_perm_b32 v83, v86, v82, s42
	v_perm_b32 v86, v86, v82, s43
	v_perm_b32 v82, v89, v85, s42
	v_perm_b32 v89, v89, v85, s43
	v_perm_b32 v85, v88, v84, s42
	v_perm_b32 v88, v88, v84, s43
	v_perm_b32 v84, v95, v91, s42
	v_perm_b32 v95, v95, v91, s43
	v_perm_b32 v91, v94, v90, s42
	v_perm_b32 v94, v94, v90, s43
	v_perm_b32 v90, v97, v93, s42
	v_perm_b32 v97, v97, v93, s43
	v_perm_b32 v93, v96, v92, s42
	v_perm_b32 v96, v96, v92, s43
	v_perm_b32 v92, v244, v224, s42
	v_perm_b32 v244, v244, v224, s43
	v_perm_b32 v224, v231, v223, s42
	v_perm_b32 v231, v231, v223, s43
	v_perm_b32 v223, v246, v226, s42
	v_perm_b32 v246, v246, v226, s43
	v_perm_b32 v226, v245, v225, s42
	v_perm_b32 v245, v245, v225, s43
	v_perm_b32 v225, v248, v228, s42
	v_perm_b32 v248, v248, v228, s43
	v_perm_b32 v228, v247, v227, s42
	v_perm_b32 v247, v247, v227, s43
	v_perm_b32 v227, v250, v230, s42
	v_perm_b32 v250, v250, v230, s43
	v_perm_b32 v230, v249, v229, s42
	v_perm_b32 v249, v249, v229, s43
	v_perm_b32 v229, v92, v20, s44
	v_perm_b32 v92, v92, v20, s45
	v_perm_b32 v20, v224, v83, s44
	v_perm_b32 v224, v224, v83, s45
	v_perm_b32 v83, v223, v82, s44
	v_perm_b32 v223, v223, v82, s45
	v_perm_b32 v82, v226, v85, s44
	v_perm_b32 v226, v226, v85, s45
	v_perm_b32 v85, v225, v84, s44
	v_perm_b32 v225, v225, v84, s45
	v_perm_b32 v84, v228, v91, s44
	v_perm_b32 v228, v228, v91, s45
	v_perm_b32 v91, v227, v90, s44
	v_perm_b32 v227, v227, v90, s45
	v_perm_b32 v90, v230, v93, s44
	v_perm_b32 v230, v230, v93, s45
	v_perm_b32 v93, v244, v87, s44
	v_perm_b32 v244, v244, v87, s45
	v_perm_b32 v87, v231, v86, s44
	v_perm_b32 v231, v231, v86, s45
	v_perm_b32 v86, v246, v89, s44
	v_perm_b32 v246, v246, v89, s45
	v_perm_b32 v89, v245, v88, s44
	v_perm_b32 v245, v245, v88, s45
	v_perm_b32 v88, v248, v95, s44
	v_perm_b32 v248, v248, v95, s45
	v_perm_b32 v95, v247, v94, s44
	v_perm_b32 v247, v247, v94, s45
	v_perm_b32 v94, v250, v97, s44
	v_perm_b32 v250, v250, v97, s45
	v_perm_b32 v97, v249, v96, s44
	v_perm_b32 v249, v249, v96, s45
	v_lshlrev_b32_e32 v22, 4, v85
	v_lshrrev_b32_e32 v23, 4, v229
	v_bfi_b32 v229, s46, v229, v22
	v_bfi_b32 v85, s46, v23, v85
	v_lshlrev_b32_e32 v22, 4, v84
	v_lshrrev_b32_e32 v23, 4, v20
	v_bfi_b32 v20, s46, v20, v22
	v_bfi_b32 v84, s46, v23, v84
	v_lshlrev_b32_e32 v22, 4, v91
	v_lshrrev_b32_e32 v23, 4, v83
	v_bfi_b32 v83, s46, v83, v22
	v_bfi_b32 v91, s46, v23, v91
	v_lshlrev_b32_e32 v22, 4, v90
	v_lshrrev_b32_e32 v23, 4, v82
	v_bfi_b32 v82, s46, v82, v22
	v_bfi_b32 v90, s46, v23, v90
	v_lshlrev_b32_e32 v22, 4, v225
	v_lshrrev_b32_e32 v23, 4, v92
	v_bfi_b32 v92, s46, v92, v22
	v_bfi_b32 v225, s46, v23, v225
	v_lshlrev_b32_e32 v22, 4, v228
	v_lshrrev_b32_e32 v23, 4, v224
	v_bfi_b32 v224, s46, v224, v22
	v_bfi_b32 v228, s46, v23, v228
	v_lshlrev_b32_e32 v22, 4, v227
	v_lshrrev_b32_e32 v23, 4, v223
	v_bfi_b32 v223, s46, v223, v22
	v_bfi_b32 v227, s46, v23, v227
	v_lshlrev_b32_e32 v22, 4, v230
	v_lshrrev_b32_e32 v23, 4, v226
	v_bfi_b32 v226, s46, v226, v22
	v_bfi_b32 v230, s46, v23, v230
	v_lshlrev_b32_e32 v22, 4, v88
	v_lshrrev_b32_e32 v23, 4, v93
	v_bfi_b32 v93, s46, v93, v22
	v_bfi_b32 v88, s46, v23, v88
	v_lshlrev_b32_e32 v22, 4, v95
	v_lshrrev_b32_e32 v23, 4, v87
	v_bfi_b32 v87, s46, v87, v22
	v_bfi_b32 v95, s46, v23, v95
	v_lshlrev_b32_e32 v22, 4, v94
	v_lshrrev_b32_e32 v23, 4, v86
	v_bfi_b32 v86, s46, v86, v22
	v_bfi_b32 v94, s46, v23, v94
	v_lshlrev_b32_e32 v22, 4, v97
	v_lshrrev_b32_e32 v23, 4, v89
	v_bfi_b32 v89, s46, v89, v22
	v_bfi_b32 v97, s46, v23, v97
	v_lshlrev_b32_e32 v22, 4, v248
	v_lshrrev_b32_e32 v23, 4, v244
	v_bfi_b32 v244, s46, v244, v22
	v_bfi_b32 v248, s46, v23, v248
	v_lshlrev_b32_e32 v22, 4, v247
	v_lshrrev_b32_e32 v23, 4, v231
	v_bfi_b32 v231, s46, v231, v22
	v_bfi_b32 v247, s46, v23, v247
	v_lshlrev_b32_e32 v22, 4, v250
	v_lshrrev_b32_e32 v23, 4, v246
	v_bfi_b32 v246, s46, v246, v22
	v_bfi_b32 v250, s46, v23, v250
	v_lshlrev_b32_e32 v22, 4, v249
	v_lshrrev_b32_e32 v23, 4, v245
	v_bfi_b32 v245, s46, v245, v22
	v_bfi_b32 v249, s46, v23, v249
	v_lshlrev_b32_e32 v22, 2, v83
	v_lshrrev_b32_e32 v23, 2, v229
	v_bfi_b32 v229, s47, v229, v22
	v_bfi_b32 v83, s47, v23, v83
	v_lshlrev_b32_e32 v22, 2, v82
	v_lshrrev_b32_e32 v23, 2, v20
	v_bfi_b32 v20, s47, v20, v22
	v_bfi_b32 v82, s47, v23, v82
	v_lshlrev_b32_e32 v22, 2, v91
	v_lshrrev_b32_e32 v23, 2, v85
	v_bfi_b32 v85, s47, v85, v22
	v_bfi_b32 v91, s47, v23, v91
	v_lshlrev_b32_e32 v22, 2, v90
	v_lshrrev_b32_e32 v23, 2, v84
	v_bfi_b32 v84, s47, v84, v22
	v_bfi_b32 v90, s47, v23, v90
	v_lshlrev_b32_e32 v22, 2, v223
	v_lshrrev_b32_e32 v23, 2, v92
	v_bfi_b32 v92, s47, v92, v22
	v_bfi_b32 v223, s47, v23, v223
	v_lshlrev_b32_e32 v22, 2, v226
	v_lshrrev_b32_e32 v23, 2, v224
	v_bfi_b32 v224, s47, v224, v22
	v_bfi_b32 v226, s47, v23, v226
	v_lshlrev_b32_e32 v22, 2, v227
	v_lshrrev_b32_e32 v23, 2, v225
	v_bfi_b32 v225, s47, v225, v22
	v_bfi_b32 v227, s47, v23, v227
	v_lshlrev_b32_e32 v22, 2, v230
	v_lshrrev_b32_e32 v23, 2, v228
	v_bfi_b32 v228, s47, v228, v22
	v_bfi_b32 v230, s47, v23, v230
	v_lshlrev_b32_e32 v22, 2, v86
	v_lshrrev_b32_e32 v23, 2, v93
	v_bfi_b32 v93, s47, v93, v22
	v_bfi_b32 v86, s47, v23, v86
	v_lshlrev_b32_e32 v22, 2, v89
	v_lshrrev_b32_e32 v23, 2, v87
	v_bfi_b32 v87, s47, v87, v22
	v_bfi_b32 v89, s47, v23, v89
	v_lshlrev_b32_e32 v22, 2, v94
	v_lshrrev_b32_e32 v23, 2, v88
	v_bfi_b32 v88, s47, v88, v22
	v_bfi_b32 v94, s47, v23, v94
	v_lshlrev_b32_e32 v22, 2, v97
	v_lshrrev_b32_e32 v23, 2, v95
	v_bfi_b32 v95, s47, v95, v22
	v_bfi_b32 v97, s47, v23, v97
	v_lshlrev_b32_e32 v22, 2, v246
	v_lshrrev_b32_e32 v23, 2, v244
; DI void a1_task(unsigned char* shm, const bf16_t* prm, const bf16_t* prt, unsigned* mask, int b, int qt, const int tid) {
;     ...
;     if (qt >= 8) {
;         const int nheld = (qt >= wid) ? ((qt - wid) >> 3) + 1 : 0;
;         bool done = false;
;     ...
;             const unsigned cand = T | (1u << bit);
;             int c = 0;
; #pragma unroll
;             for (int jt = 0; jt < 8; ++jt) {
;                 if (jt < nheld) {
; #pragma unroll
;                     for (int i = 0; i < 16; ++i) c += (key[jt][i] >= cand) ? 1 : 0;
;                 }
;             }
	v_bfi_b32 v244, s47, v244, v22
	v_bfi_b32 v246, s47, v23, v246
	v_lshlrev_b32_e32 v22, 2, v245
	v_lshrrev_b32_e32 v23, 2, v231
	v_bfi_b32 v231, s47, v231, v22
	v_bfi_b32 v245, s47, v23, v245
	v_lshlrev_b32_e32 v22, 2, v250
	v_lshrrev_b32_e32 v23, 2, v248
	v_bfi_b32 v248, s47, v248, v22
	v_bfi_b32 v250, s47, v23, v250
	v_lshlrev_b32_e32 v22, 2, v249
	v_lshrrev_b32_e32 v23, 2, v247
	v_bfi_b32 v247, s47, v247, v22
	v_bfi_b32 v249, s47, v23, v249
	v_lshlrev_b32_e32 v22, 1, v20
	v_lshrrev_b32_e32 v23, 1, v229
	v_bfi_b32 v229, s48, v229, v22
	v_bfi_b32 v20, s48, v23, v20
	v_lshlrev_b32_e32 v22, 1, v82
	v_lshrrev_b32_e32 v23, 1, v83
	v_bfi_b32 v83, s48, v83, v22
	v_bfi_b32 v82, s48, v23, v82
	v_lshlrev_b32_e32 v22, 1, v84
	v_lshrrev_b32_e32 v23, 1, v85
	v_bfi_b32 v85, s48, v85, v22
	v_bfi_b32 v84, s48, v23, v84
	v_lshlrev_b32_e32 v22, 1, v90
	v_lshrrev_b32_e32 v23, 1, v91
	v_bfi_b32 v91, s48, v91, v22
	v_bfi_b32 v90, s48, v23, v90
	v_lshlrev_b32_e32 v22, 1, v224
	v_lshrrev_b32_e32 v23, 1, v92
	v_bfi_b32 v92, s48, v92, v22
	v_bfi_b32 v224, s48, v23, v224
	v_lshlrev_b32_e32 v22, 1, v226
	v_lshrrev_b32_e32 v23, 1, v223
	v_bfi_b32 v223, s48, v223, v22
	v_bfi_b32 v226, s48, v23, v226
	v_lshlrev_b32_e32 v22, 1, v228
	v_lshrrev_b32_e32 v23, 1, v225
	v_bfi_b32 v225, s48, v225, v22
	v_bfi_b32 v228, s48, v23, v228
	v_lshlrev_b32_e32 v22, 1, v230
	v_lshrrev_b32_e32 v23, 1, v227
	v_bfi_b32 v227, s48, v227, v22
	v_bfi_b32 v230, s48, v23, v230
	v_lshlrev_b32_e32 v22, 1, v87
	v_lshrrev_b32_e32 v23, 1, v93
	v_bfi_b32 v93, s48, v93, v22
	v_bfi_b32 v87, s48, v23, v87
	v_lshlrev_b32_e32 v22, 1, v89
	v_lshrrev_b32_e32 v23, 1, v86
	v_bfi_b32 v86, s48, v86, v22
	v_bfi_b32 v89, s48, v23, v89
	v_lshlrev_b32_e32 v22, 1, v95
	v_lshrrev_b32_e32 v23, 1, v88
	v_bfi_b32 v88, s48, v88, v22
	v_bfi_b32 v95, s48, v23, v95
	v_lshlrev_b32_e32 v22, 1, v97
	v_lshrrev_b32_e32 v23, 1, v94
	v_bfi_b32 v94, s48, v94, v22
	v_bfi_b32 v97, s48, v23, v97
	v_lshlrev_b32_e32 v22, 1, v231
	v_lshrrev_b32_e32 v23, 1, v244
	v_bfi_b32 v244, s48, v244, v22
	v_bfi_b32 v231, s48, v23, v231
	v_lshlrev_b32_e32 v22, 1, v245
	v_lshrrev_b32_e32 v23, 1, v246
	v_bfi_b32 v246, s48, v246, v22
	v_bfi_b32 v245, s48, v23, v245
	v_lshlrev_b32_e32 v22, 1, v247
	v_lshrrev_b32_e32 v23, 1, v248
	v_bfi_b32 v248, s48, v248, v22
	v_bfi_b32 v247, s48, v23, v247
	v_lshlrev_b32_e32 v22, 1, v249
	v_lshrrev_b32_e32 v23, 1, v250
	v_bfi_b32 v250, s48, v250, v22
	v_bfi_b32 v249, s48, v23, v249
	s_cmp_lt_i32 s41, 48
	s_cbranch_scc1 .Lbs_tr_done
	v_perm_b32 v21, v35, v51, s42
	v_perm_b32 v35, v35, v51, s43
	v_perm_b32 v51, v34, v50, s42
	v_perm_b32 v34, v34, v50, s43
	v_perm_b32 v50, v17, v53, s42
	v_perm_b32 v17, v17, v53, s43
	v_perm_b32 v53, v16, v52, s42
	v_perm_b32 v16, v16, v52, s43
	v_perm_b32 v52, v15, v55, s42
	v_perm_b32 v15, v15, v55, s43
	v_perm_b32 v55, v14, v54, s42
	v_perm_b32 v14, v14, v54, s43
	v_perm_b32 v54, v13, v57, s42
	v_perm_b32 v13, v13, v57, s43
	v_perm_b32 v57, v12, v56, s42
	v_perm_b32 v12, v12, v56, s43
	v_perm_b32 v56, v11, v59, s42
	v_perm_b32 v11, v11, v59, s43
	v_perm_b32 v59, v10, v58, s42
	v_perm_b32 v10, v10, v58, s43
	v_perm_b32 v58, v9, v61, s42
	v_perm_b32 v9, v9, v61, s43
	v_perm_b32 v61, v8, v60, s42
	v_perm_b32 v8, v8, v60, s43
	v_perm_b32 v60, v7, v63, s42
	v_perm_b32 v7, v7, v63, s43
	v_perm_b32 v63, v6, v62, s42
	v_perm_b32 v6, v6, v62, s43
	v_perm_b32 v62, v5, v65, s42
	v_perm_b32 v5, v5, v65, s43
	v_perm_b32 v65, v4, v64, s42
	v_perm_b32 v4, v4, v64, s43
	v_perm_b32 v64, v56, v21, s44
	v_perm_b32 v56, v56, v21, s45
	v_perm_b32 v21, v59, v51, s44
	v_perm_b32 v59, v59, v51, s45
	v_perm_b32 v51, v58, v50, s44
	v_perm_b32 v58, v58, v50, s45
	v_perm_b32 v50, v61, v53, s44
	v_perm_b32 v61, v61, v53, s45
	v_perm_b32 v53, v60, v52, s44
	v_perm_b32 v60, v60, v52, s45
	v_perm_b32 v52, v63, v55, s44
	v_perm_b32 v63, v63, v55, s45
	v_perm_b32 v55, v62, v54, s44
	v_perm_b32 v62, v62, v54, s45
	v_perm_b32 v54, v65, v57, s44
	v_perm_b32 v65, v65, v57, s45
	v_perm_b32 v57, v11, v35, s44
	v_perm_b32 v11, v11, v35, s45
	v_perm_b32 v35, v10, v34, s44
	v_perm_b32 v10, v10, v34, s45
	v_perm_b32 v34, v9, v17, s44
	v_perm_b32 v9, v9, v17, s45
	v_perm_b32 v17, v8, v16, s44
	v_perm_b32 v8, v8, v16, s45
	v_perm_b32 v16, v7, v15, s44
	v_perm_b32 v7, v7, v15, s45
	v_perm_b32 v15, v6, v14, s44
	v_perm_b32 v6, v6, v14, s45
	v_perm_b32 v14, v5, v13, s44
	v_perm_b32 v5, v5, v13, s45
	v_perm_b32 v13, v4, v12, s44
	v_perm_b32 v4, v4, v12, s45
	v_lshlrev_b32_e32 v22, 4, v53
	v_lshrrev_b32_e32 v23, 4, v64
	v_bfi_b32 v64, s46, v64, v22
	v_bfi_b32 v53, s46, v23, v53
	v_lshlrev_b32_e32 v22, 4, v52
	v_lshrrev_b32_e32 v23, 4, v21
	v_bfi_b32 v21, s46, v21, v22
	v_bfi_b32 v52, s46, v23, v52
	v_lshlrev_b32_e32 v22, 4, v55
	v_lshrrev_b32_e32 v23, 4, v51
	v_bfi_b32 v51, s46, v51, v22
	v_bfi_b32 v55, s46, v23, v55
	v_lshlrev_b32_e32 v22, 4, v54
	v_lshrrev_b32_e32 v23, 4, v50
	v_bfi_b32 v50, s46, v50, v22
	v_bfi_b32 v54, s46, v23, v54
	v_lshlrev_b32_e32 v22, 4, v60
	v_lshrrev_b32_e32 v23, 4, v56
	v_bfi_b32 v56, s46, v56, v22
	v_bfi_b32 v60, s46, v23, v60
	v_lshlrev_b32_e32 v22, 4, v63
	v_lshrrev_b32_e32 v23, 4, v59
	v_bfi_b32 v59, s46, v59, v22
	v_bfi_b32 v63, s46, v23, v63
	v_lshlrev_b32_e32 v22, 4, v62
	v_lshrrev_b32_e32 v23, 4, v58
	v_bfi_b32 v58, s46, v58, v22
	v_bfi_b32 v62, s46, v23, v62
	v_lshlrev_b32_e32 v22, 4, v65
	v_lshrrev_b32_e32 v23, 4, v61
	v_bfi_b32 v61, s46, v61, v22
	v_bfi_b32 v65, s46, v23, v65
	v_lshlrev_b32_e32 v22, 4, v16
	v_lshrrev_b32_e32 v23, 4, v57
	v_bfi_b32 v57, s46, v57, v22
	v_bfi_b32 v16, s46, v23, v16
	v_lshlrev_b32_e32 v22, 4, v15
	v_lshrrev_b32_e32 v23, 4, v35
	v_bfi_b32 v35, s46, v35, v22
; DI void a1_task(unsigned char* shm, const bf16_t* prm, const bf16_t* prt, unsigned* mask, int b, int qt, const int tid) {
;     ...
;     unsigned T = 0u;
;     if (qt >= 8) {
;         const int nheld = (qt >= wid) ? ((qt - wid) >> 3) + 1 : 0;
;         bool done = false;
;     ...
;             const unsigned cand = T | (1u << bit);
;             int c = 0;
; #pragma unroll
;             for (int jt = 0; jt < 8; ++jt) {
;                 if (jt < nheld) {
; #pragma unroll
;                     for (int i = 0; i < 16; ++i) c += (key[jt][i] >= cand) ? 1 : 0;
;                 }
;             }
	v_bfi_b32 v15, s46, v23, v15
	v_lshlrev_b32_e32 v22, 4, v14
	v_lshrrev_b32_e32 v23, 4, v34
	v_bfi_b32 v34, s46, v34, v22
	v_bfi_b32 v14, s46, v23, v14
	v_lshlrev_b32_e32 v22, 4, v13
	v_lshrrev_b32_e32 v23, 4, v17
	v_bfi_b32 v17, s46, v17, v22
	v_bfi_b32 v13, s46, v23, v13
	v_lshlrev_b32_e32 v22, 4, v7
	v_lshrrev_b32_e32 v23, 4, v11
	v_bfi_b32 v11, s46, v11, v22
	v_bfi_b32 v7, s46, v23, v7
	v_lshlrev_b32_e32 v22, 4, v6
	v_lshrrev_b32_e32 v23, 4, v10
	v_bfi_b32 v10, s46, v10, v22
	v_bfi_b32 v6, s46, v23, v6
	v_lshlrev_b32_e32 v22, 4, v5
	v_lshrrev_b32_e32 v23, 4, v9
	v_bfi_b32 v9, s46, v9, v22
	v_bfi_b32 v5, s46, v23, v5
	v_lshlrev_b32_e32 v22, 4, v4
	v_lshrrev_b32_e32 v23, 4, v8
	v_bfi_b32 v8, s46, v8, v22
	v_bfi_b32 v4, s46, v23, v4
	v_lshlrev_b32_e32 v22, 2, v51
	v_lshrrev_b32_e32 v23, 2, v64
	v_bfi_b32 v64, s47, v64, v22
	v_bfi_b32 v51, s47, v23, v51
	v_lshlrev_b32_e32 v22, 2, v50
	v_lshrrev_b32_e32 v23, 2, v21
	v_bfi_b32 v21, s47, v21, v22
	v_bfi_b32 v50, s47, v23, v50
	v_lshlrev_b32_e32 v22, 2, v55
	v_lshrrev_b32_e32 v23, 2, v53
	v_bfi_b32 v53, s47, v53, v22
	v_bfi_b32 v55, s47, v23, v55
	v_lshlrev_b32_e32 v22, 2, v54
	v_lshrrev_b32_e32 v23, 2, v52
	v_bfi_b32 v52, s47, v52, v22
	v_bfi_b32 v54, s47, v23, v54
	v_lshlrev_b32_e32 v22, 2, v58
	v_lshrrev_b32_e32 v23, 2, v56
	v_bfi_b32 v56, s47, v56, v22
	v_bfi_b32 v58, s47, v23, v58
	v_lshlrev_b32_e32 v22, 2, v61
	v_lshrrev_b32_e32 v23, 2, v59
	v_bfi_b32 v59, s47, v59, v22
	v_bfi_b32 v61, s47, v23, v61
	v_lshlrev_b32_e32 v22, 2, v62
	v_lshrrev_b32_e32 v23, 2, v60
	v_bfi_b32 v60, s47, v60, v22
	v_bfi_b32 v62, s47, v23, v62
	v_lshlrev_b32_e32 v22, 2, v65
	v_lshrrev_b32_e32 v23, 2, v63
	v_bfi_b32 v63, s47, v63, v22
	v_bfi_b32 v65, s47, v23, v65
	v_lshlrev_b32_e32 v22, 2, v34
	v_lshrrev_b32_e32 v23, 2, v57
	v_bfi_b32 v57, s47, v57, v22
	v_bfi_b32 v34, s47, v23, v34
	v_lshlrev_b32_e32 v22, 2, v17
	v_lshrrev_b32_e32 v23, 2, v35
	v_bfi_b32 v35, s47, v35, v22
	v_bfi_b32 v17, s47, v23, v17
	v_lshlrev_b32_e32 v22, 2, v14
	v_lshrrev_b32_e32 v23, 2, v16
	v_bfi_b32 v16, s47, v16, v22
	v_bfi_b32 v14, s47, v23, v14
	v_lshlrev_b32_e32 v22, 2, v13
	v_lshrrev_b32_e32 v23, 2, v15
	v_bfi_b32 v15, s47, v15, v22
	v_bfi_b32 v13, s47, v23, v13
	v_lshlrev_b32_e32 v22, 2, v9
	v_lshrrev_b32_e32 v23, 2, v11
	v_bfi_b32 v11, s47, v11, v22
	v_bfi_b32 v9, s47, v23, v9
	v_lshlrev_b32_e32 v22, 2, v8
	v_lshrrev_b32_e32 v23, 2, v10
	v_bfi_b32 v10, s47, v10, v22
	v_bfi_b32 v8, s47, v23, v8
	v_lshlrev_b32_e32 v22, 2, v5
	v_lshrrev_b32_e32 v23, 2, v7
	v_bfi_b32 v7, s47, v7, v22
	v_bfi_b32 v5, s47, v23, v5
	v_lshlrev_b32_e32 v22, 2, v4
	v_lshrrev_b32_e32 v23, 2, v6
	v_bfi_b32 v6, s47, v6, v22
	v_bfi_b32 v4, s47, v23, v4
	v_lshlrev_b32_e32 v22, 1, v21
	v_lshrrev_b32_e32 v23, 1, v64
	v_bfi_b32 v64, s48, v64, v22
	v_bfi_b32 v21, s48, v23, v21
	v_lshlrev_b32_e32 v22, 1, v50
	v_lshrrev_b32_e32 v23, 1, v51
	v_bfi_b32 v51, s48, v51, v22
	v_bfi_b32 v50, s48, v23, v50
	v_lshlrev_b32_e32 v22, 1, v52
	v_lshrrev_b32_e32 v23, 1, v53
	v_bfi_b32 v53, s48, v53, v22
	v_bfi_b32 v52, s48, v23, v52
	v_lshlrev_b32_e32 v22, 1, v54
	v_lshrrev_b32_e32 v23, 1, v55
	v_bfi_b32 v55, s48, v55, v22
	v_bfi_b32 v54, s48, v23, v54
	v_lshlrev_b32_e32 v22, 1, v59
	v_lshrrev_b32_e32 v23, 1, v56
	v_bfi_b32 v56, s48, v56, v22
	v_bfi_b32 v59, s48, v23, v59
	v_lshlrev_b32_e32 v22, 1, v61
	v_lshrrev_b32_e32 v23, 1, v58
	v_bfi_b32 v58, s48, v58, v22
	v_bfi_b32 v61, s48, v23, v61
	v_lshlrev_b32_e32 v22, 1, v63
	v_lshrrev_b32_e32 v23, 1, v60
	v_bfi_b32 v60, s48, v60, v22
	v_bfi_b32 v63, s48, v23, v63
	v_lshlrev_b32_e32 v22, 1, v65
	v_lshrrev_b32_e32 v23, 1, v62
	v_bfi_b32 v62, s48, v62, v22
	v_bfi_b32 v65, s48, v23, v65
	v_lshlrev_b32_e32 v22, 1, v35
	v_lshrrev_b32_e32 v23, 1, v57
	v_bfi_b32 v57, s48, v57, v22
	v_bfi_b32 v35, s48, v23, v35
	v_lshlrev_b32_e32 v22, 1, v17
	v_lshrrev_b32_e32 v23, 1, v34
	v_bfi_b32 v34, s48, v34, v22
	v_bfi_b32 v17, s48, v23, v17
	v_lshlrev_b32_e32 v22, 1, v15
	v_lshrrev_b32_e32 v23, 1, v16
	v_bfi_b32 v16, s48, v16, v22
	v_bfi_b32 v15, s48, v23, v15
	v_lshlrev_b32_e32 v22, 1, v13
	v_lshrrev_b32_e32 v23, 1, v14
	v_bfi_b32 v14, s48, v14, v22
	v_bfi_b32 v13, s48, v23, v13
	v_lshlrev_b32_e32 v22, 1, v10
	v_lshrrev_b32_e32 v23, 1, v11
	v_bfi_b32 v11, s48, v11, v22
	v_bfi_b32 v10, s48, v23, v10
	v_lshlrev_b32_e32 v22, 1, v8
	v_lshrrev_b32_e32 v23, 1, v9
	v_bfi_b32 v9, s48, v9, v22
	v_bfi_b32 v8, s48, v23, v8
	v_lshlrev_b32_e32 v22, 1, v6
	v_lshrrev_b32_e32 v23, 1, v7
	v_bfi_b32 v7, s48, v7, v22
	v_bfi_b32 v6, s48, v23, v6
	v_lshlrev_b32_e32 v22, 1, v4
	v_lshrrev_b32_e32 v23, 1, v5
	v_bfi_b32 v5, s48, v5, v22
	v_bfi_b32 v4, s48, v23, v4
.Lbs_tr_done:
	s_cmp_lt_i32 s41, 8
	s_cselect_b32 s0, 0xffff, -1
	v_mov_b32_e32 v24, s0
	v_mov_b32_e32 v28, 0
	s_cmp_lt_i32 s41, 24
	s_cselect_b32 s0, 0xffff, -1
	v_mov_b32_e32 v25, s0
	v_mov_b32_e32 v29, 0
	s_cmp_lt_i32 s41, 40
	s_cselect_b32 s0, 0xffff, -1
	v_mov_b32_e32 v26, s0
	v_mov_b32_e32 v30, 0
	s_cmp_lt_i32 s41, 56
	s_cselect_b32 s0, 0xffff, -1
	v_mov_b32_e32 v27, s0
	v_mov_b32_e32 v31, 0
	v_mov_b32_e32 v41, 0
	s_movk_i32 s42, 0xff
	s_movk_i32 s43, 0x100
	s_mov_b64 s[44:45], 0
	s_mov_b64 s[46:47], 0
	v_and_b32_e32 v32, v24, v172
	v_bcnt_u32_b32 v38, v32, v41
	s_cmp_lt_i32 s41, 16
	s_cbranch_scc1 .Lbs_c31
	v_and_b32_e32 v33, v25, v221
	v_bcnt_u32_b32 v38, v33, v38
	s_cmp_lt_i32 s41, 32
	s_cbranch_scc1 .Lbs_c31
	v_and_b32_e32 v36, v26, v249
	v_bcnt_u32_b32 v38, v36, v38
	s_cmp_lt_i32 s41, 48
	s_cbranch_scc1 .Lbs_c31
	v_and_b32_e32 v37, v27, v4
	v_bcnt_u32_b32 v38, v37, v38
; DI void a1_task(unsigned char* shm, const bf16_t* prm, const bf16_t* prt, unsigned* mask, int b, int qt, const int tid) {
;     ...
;     unsigned T = 0u;
;     if (qt >= 8) {
;         const int nheld = (qt >= wid) ? ((qt - wid) >> 3) + 1 : 0;
;         bool done = false;
;     ...
;             const unsigned cand = T | (1u << bit);
;             int c = 0;
; #pragma unroll
;             for (int jt = 0; jt < 8; ++jt) {
;                 if (jt < nheld) {
; #pragma unroll
;                     for (int i = 0; i < 16; ++i) c += (key[jt][i] >= cand) ? 1 : 0;
;                 }
;             }
;             c += __shfl_xor(c, 32);
;             if (h == 0 && c) atomicAdd(&cnt[(31 - bit) * 32 + r], (unsigned)c);
;             __syncthreads();
;             const unsigned tot = cnt[(31 - bit) * 32 + r];
;             if (!done) { if (tot >= 256u) T = cand; if (tot == 256u) done = true; }
;             if (__ballot(!done) == 0ull) break;
;         }
;     }
.Lbs_c31:
	v_mov_b32_e32 v39, v38
	v_mov_b32_e32 v40, v38
	s_nop 1
	v_permlane32_swap_b32_e32 v39, v40
	v_add_u32_e32 v39, v39, v40
	v_cmp_ne_u32_e32 vcc, 0, v39
	s_and_b64 vcc, vcc, s[58:59]
	s_and_saveexec_b64 s[54:55], vcc
	ds_add_u32 v136, v39
	s_mov_b64 exec, s[54:55]
	s_waitcnt lgkmcnt(0)
	s_barrier
	ds_read_b32 v42, v136
	s_waitcnt lgkmcnt(0)
	v_cmp_lt_u32_e64 s[48:49], s42, v42
	v_cmp_eq_u32_e32 vcc, s43, v42
	s_andn2_b64 s[50:51], s[48:49], s[44:45]
	s_or_b64 s[48:49], s[48:49], s[44:45]
	s_andn2_b64 s[52:53], exec, s[48:49]
	s_or_b64 s[46:47], s[46:47], s[50:51]
	s_or_b64 s[44:45], s[44:45], vcc
	v_cndmask_b32_e64 v41, v41, v38, s[52:53]
	v_cndmask_b32_e64 v43, 0, v32, s[52:53]
	v_or_b32_e32 v28, v28, v43
	v_xor_b32_e32 v43, v24, v43
	v_cndmask_b32_e64 v24, v43, v32, s[50:51]
	s_cmp_lt_i32 s41, 16
	s_cbranch_scc1 .Lbs_u31
	v_cndmask_b32_e64 v43, 0, v33, s[52:53]
	v_or_b32_e32 v29, v29, v43
	v_xor_b32_e32 v43, v25, v43
	v_cndmask_b32_e64 v25, v43, v33, s[50:51]
	s_cmp_lt_i32 s41, 32
	s_cbranch_scc1 .Lbs_u31
	v_cndmask_b32_e64 v43, 0, v36, s[52:53]
	v_or_b32_e32 v30, v30, v43
	v_xor_b32_e32 v43, v26, v43
	v_cndmask_b32_e64 v26, v43, v36, s[50:51]
	s_cmp_lt_i32 s41, 48
	s_cbranch_scc1 .Lbs_u31
	v_cndmask_b32_e64 v43, 0, v37, s[52:53]
	v_or_b32_e32 v31, v31, v43
	v_xor_b32_e32 v43, v27, v43
	v_cndmask_b32_e64 v27, v43, v37, s[50:51]
.Lbs_u31:
	s_andn2_b64 s[48:49], exec, s[44:45]
	s_cbranch_scc0 .Lbs_end
	v_and_b32_e32 v32, v24, v173
	v_bcnt_u32_b32 v38, v32, v41
	s_cmp_lt_i32 s41, 16
	s_cbranch_scc1 .Lbs_c30
	v_and_b32_e32 v33, v25, v222
	v_bcnt_u32_b32 v38, v33, v38
	s_cmp_lt_i32 s41, 32
	s_cbranch_scc1 .Lbs_c30
	v_and_b32_e32 v36, v26, v250
	v_bcnt_u32_b32 v38, v36, v38
	s_cmp_lt_i32 s41, 48
	s_cbranch_scc1 .Lbs_c30
	v_and_b32_e32 v37, v27, v5
	v_bcnt_u32_b32 v38, v37, v38
.Lbs_c30:
	v_mov_b32_e32 v39, v38
	v_mov_b32_e32 v40, v38
	s_nop 1
	v_permlane32_swap_b32_e32 v39, v40
	v_add_u32_e32 v39, v39, v40
	v_cmp_ne_u32_e32 vcc, 0, v39
	s_and_b64 vcc, vcc, s[58:59]
	s_and_saveexec_b64 s[54:55], vcc
	ds_add_u32 v136, v39 offset:128
	s_mov_b64 exec, s[54:55]
	s_waitcnt lgkmcnt(0)
	s_barrier
	ds_read_b32 v42, v136 offset:128
	s_waitcnt lgkmcnt(0)
	v_cmp_lt_u32_e64 s[48:49], s42, v42
	v_cmp_eq_u32_e32 vcc, s43, v42
	s_andn2_b64 s[50:51], s[48:49], s[44:45]
	s_or_b64 s[48:49], s[48:49], s[44:45]
	s_andn2_b64 s[52:53], exec, s[48:49]
	s_or_b64 s[46:47], s[46:47], s[50:51]
	s_or_b64 s[44:45], s[44:45], vcc
	v_cndmask_b32_e64 v41, v41, v38, s[52:53]
	v_cndmask_b32_e64 v43, 0, v32, s[52:53]
	v_or_b32_e32 v28, v28, v43
	v_xor_b32_e32 v43, v24, v43
	v_cndmask_b32_e64 v24, v43, v32, s[50:51]
	s_cmp_lt_i32 s41, 16
	s_cbranch_scc1 .Lbs_u30
	v_cndmask_b32_e64 v43, 0, v33, s[52:53]
	v_or_b32_e32 v29, v29, v43
	v_xor_b32_e32 v43, v25, v43
	v_cndmask_b32_e64 v25, v43, v33, s[50:51]
	s_cmp_lt_i32 s41, 32
	s_cbranch_scc1 .Lbs_u30
	v_cndmask_b32_e64 v43, 0, v36, s[52:53]
	v_or_b32_e32 v30, v30, v43
	v_xor_b32_e32 v43, v26, v43
	v_cndmask_b32_e64 v26, v43, v36, s[50:51]
	s_cmp_lt_i32 s41, 48
	s_cbranch_scc1 .Lbs_u30
	v_cndmask_b32_e64 v43, 0, v37, s[52:53]
	v_or_b32_e32 v31, v31, v43
	v_xor_b32_e32 v43, v27, v43
	v_cndmask_b32_e64 v27, v43, v37, s[50:51]
.Lbs_u30:
	s_andn2_b64 s[48:49], exec, s[44:45]
	s_cbranch_scc0 .Lbs_end
	v_and_b32_e32 v32, v24, v170
	v_bcnt_u32_b32 v38, v32, v41
	s_cmp_lt_i32 s41, 16
	s_cbranch_scc1 .Lbs_c29
	v_and_b32_e32 v33, v25, v219
	v_bcnt_u32_b32 v38, v33, v38
	s_cmp_lt_i32 s41, 32
	s_cbranch_scc1 .Lbs_c29
	v_and_b32_e32 v36, v26, v247
	v_bcnt_u32_b32 v38, v36, v38
	s_cmp_lt_i32 s41, 48
	s_cbranch_scc1 .Lbs_c29
	v_and_b32_e32 v37, v27, v6
	v_bcnt_u32_b32 v38, v37, v38
.Lbs_c29:
	v_mov_b32_e32 v39, v38
	v_mov_b32_e32 v40, v38
	s_nop 1
	v_permlane32_swap_b32_e32 v39, v40
	v_add_u32_e32 v39, v39, v40
	v_cmp_ne_u32_e32 vcc, 0, v39
	s_and_b64 vcc, vcc, s[58:59]
	s_and_saveexec_b64 s[54:55], vcc
	ds_add_u32 v136, v39 offset:256
	s_mov_b64 exec, s[54:55]
	s_waitcnt lgkmcnt(0)
	s_barrier
	ds_read_b32 v42, v136 offset:256
	s_waitcnt lgkmcnt(0)
	v_cmp_lt_u32_e64 s[48:49], s42, v42
	v_cmp_eq_u32_e32 vcc, s43, v42
	s_andn2_b64 s[50:51], s[48:49], s[44:45]
	s_or_b64 s[48:49], s[48:49], s[44:45]
	s_andn2_b64 s[52:53], exec, s[48:49]
	s_or_b64 s[46:47], s[46:47], s[50:51]
	s_or_b64 s[44:45], s[44:45], vcc
	v_cndmask_b32_e64 v41, v41, v38, s[52:53]
	v_cndmask_b32_e64 v43, 0, v32, s[52:53]
	v_or_b32_e32 v28, v28, v43
	v_xor_b32_e32 v43, v24, v43
	v_cndmask_b32_e64 v24, v43, v32, s[50:51]
	s_cmp_lt_i32 s41, 16
	s_cbranch_scc1 .Lbs_u29
	v_cndmask_b32_e64 v43, 0, v33, s[52:53]
	v_or_b32_e32 v29, v29, v43
	v_xor_b32_e32 v43, v25, v43
	v_cndmask_b32_e64 v25, v43, v33, s[50:51]
	s_cmp_lt_i32 s41, 32
	s_cbranch_scc1 .Lbs_u29
	v_cndmask_b32_e64 v43, 0, v36, s[52:53]
	v_or_b32_e32 v30, v30, v43
	v_xor_b32_e32 v43, v26, v43
	v_cndmask_b32_e64 v26, v43, v36, s[50:51]
	s_cmp_lt_i32 s41, 48
	s_cbranch_scc1 .Lbs_u29
	v_cndmask_b32_e64 v43, 0, v37, s[52:53]
	v_or_b32_e32 v31, v31, v43
	v_xor_b32_e32 v43, v27, v43
	v_cndmask_b32_e64 v27, v43, v37, s[50:51]
.Lbs_u29:
	s_andn2_b64 s[48:49], exec, s[44:45]
	s_cbranch_scc0 .Lbs_end
	v_and_b32_e32 v32, v24, v171
	v_bcnt_u32_b32 v38, v32, v41
	s_cmp_lt_i32 s41, 16
	s_cbranch_scc1 .Lbs_c28
	v_and_b32_e32 v33, v25, v220
	v_bcnt_u32_b32 v38, v33, v38
	s_cmp_lt_i32 s41, 32
	s_cbranch_scc1 .Lbs_c28
	v_and_b32_e32 v36, v26, v248
	v_bcnt_u32_b32 v38, v36, v38
	s_cmp_lt_i32 s41, 48
	s_cbranch_scc1 .Lbs_c28
	v_and_b32_e32 v37, v27, v7
	v_bcnt_u32_b32 v38, v37, v38
; DI void a1_task(unsigned char* shm, const bf16_t* prm, const bf16_t* prt, unsigned* mask, int b, int qt, const int tid) {
;     ...
;             const unsigned cand = T | (1u << bit);
;             int c = 0;
; #pragma unroll
;             for (int jt = 0; jt < 8; ++jt) {
;                 if (jt < nheld) {
; #pragma unroll
;                     for (int i = 0; i < 16; ++i) c += (key[jt][i] >= cand) ? 1 : 0;
;                 }
;             }
;             c += __shfl_xor(c, 32);
;             if (h == 0 && c) atomicAdd(&cnt[(31 - bit) * 32 + r], (unsigned)c);
;             __syncthreads();
;             const unsigned tot = cnt[(31 - bit) * 32 + r];
;             if (!done) { if (tot >= 256u) T = cand; if (tot == 256u) done = true; }
;             if (__ballot(!done) == 0ull) break;
;         }
.Lbs_c28:
	v_mov_b32_e32 v39, v38
	v_mov_b32_e32 v40, v38
	s_nop 1
	v_permlane32_swap_b32_e32 v39, v40
	v_add_u32_e32 v39, v39, v40
	v_cmp_ne_u32_e32 vcc, 0, v39
	s_and_b64 vcc, vcc, s[58:59]
	s_and_saveexec_b64 s[54:55], vcc
	ds_add_u32 v136, v39 offset:384
	s_mov_b64 exec, s[54:55]
	s_waitcnt lgkmcnt(0)
	s_barrier
	ds_read_b32 v42, v136 offset:384
	s_waitcnt lgkmcnt(0)
	v_cmp_lt_u32_e64 s[48:49], s42, v42
	v_cmp_eq_u32_e32 vcc, s43, v42
	s_andn2_b64 s[50:51], s[48:49], s[44:45]
	s_or_b64 s[48:49], s[48:49], s[44:45]
	s_andn2_b64 s[52:53], exec, s[48:49]
	s_or_b64 s[46:47], s[46:47], s[50:51]
	s_or_b64 s[44:45], s[44:45], vcc
	v_cndmask_b32_e64 v41, v41, v38, s[52:53]
	v_cndmask_b32_e64 v43, 0, v32, s[52:53]
	v_or_b32_e32 v28, v28, v43
	v_xor_b32_e32 v43, v24, v43
	v_cndmask_b32_e64 v24, v43, v32, s[50:51]
	s_cmp_lt_i32 s41, 16
	s_cbranch_scc1 .Lbs_u28
	v_cndmask_b32_e64 v43, 0, v33, s[52:53]
	v_or_b32_e32 v29, v29, v43
	v_xor_b32_e32 v43, v25, v43
	v_cndmask_b32_e64 v25, v43, v33, s[50:51]
	s_cmp_lt_i32 s41, 32
	s_cbranch_scc1 .Lbs_u28
	v_cndmask_b32_e64 v43, 0, v36, s[52:53]
	v_or_b32_e32 v30, v30, v43
	v_xor_b32_e32 v43, v26, v43
	v_cndmask_b32_e64 v26, v43, v36, s[50:51]
	s_cmp_lt_i32 s41, 48
	s_cbranch_scc1 .Lbs_u28
	v_cndmask_b32_e64 v43, 0, v37, s[52:53]
	v_or_b32_e32 v31, v31, v43
	v_xor_b32_e32 v43, v27, v43
	v_cndmask_b32_e64 v27, v43, v37, s[50:51]
.Lbs_u28:
	s_andn2_b64 s[48:49], exec, s[44:45]
	s_cbranch_scc0 .Lbs_end
	v_and_b32_e32 v32, v24, v168
	v_bcnt_u32_b32 v38, v32, v41
	s_cmp_lt_i32 s41, 16
	s_cbranch_scc1 .Lbs_c27
	v_and_b32_e32 v33, v25, v217
	v_bcnt_u32_b32 v38, v33, v38
	s_cmp_lt_i32 s41, 32
	s_cbranch_scc1 .Lbs_c27
	v_and_b32_e32 v36, v26, v245
	v_bcnt_u32_b32 v38, v36, v38
	s_cmp_lt_i32 s41, 48
	s_cbranch_scc1 .Lbs_c27
	v_and_b32_e32 v37, v27, v8
	v_bcnt_u32_b32 v38, v37, v38
.Lbs_c27:
	v_mov_b32_e32 v39, v38
	v_mov_b32_e32 v40, v38
	s_nop 1
	v_permlane32_swap_b32_e32 v39, v40
	v_add_u32_e32 v39, v39, v40
	v_cmp_ne_u32_e32 vcc, 0, v39
	s_and_b64 vcc, vcc, s[58:59]
	s_and_saveexec_b64 s[54:55], vcc
	ds_add_u32 v136, v39 offset:512
	s_mov_b64 exec, s[54:55]
	s_waitcnt lgkmcnt(0)
	s_barrier
	ds_read_b32 v42, v136 offset:512
	s_waitcnt lgkmcnt(0)
	v_cmp_lt_u32_e64 s[48:49], s42, v42
	v_cmp_eq_u32_e32 vcc, s43, v42
	s_andn2_b64 s[50:51], s[48:49], s[44:45]
	s_or_b64 s[48:49], s[48:49], s[44:45]
	s_andn2_b64 s[52:53], exec, s[48:49]
	s_or_b64 s[46:47], s[46:47], s[50:51]
	s_or_b64 s[44:45], s[44:45], vcc
	v_cndmask_b32_e64 v41, v41, v38, s[52:53]
	v_cndmask_b32_e64 v43, 0, v32, s[52:53]
	v_or_b32_e32 v28, v28, v43
	v_xor_b32_e32 v43, v24, v43
	v_cndmask_b32_e64 v24, v43, v32, s[50:51]
	s_cmp_lt_i32 s41, 16
	s_cbranch_scc1 .Lbs_u27
	v_cndmask_b32_e64 v43, 0, v33, s[52:53]
	v_or_b32_e32 v29, v29, v43
	v_xor_b32_e32 v43, v25, v43
	v_cndmask_b32_e64 v25, v43, v33, s[50:51]
	s_cmp_lt_i32 s41, 32
	s_cbranch_scc1 .Lbs_u27
	v_cndmask_b32_e64 v43, 0, v36, s[52:53]
	v_or_b32_e32 v30, v30, v43
	v_xor_b32_e32 v43, v26, v43
	v_cndmask_b32_e64 v26, v43, v36, s[50:51]
	s_cmp_lt_i32 s41, 48
	s_cbranch_scc1 .Lbs_u27
	v_cndmask_b32_e64 v43, 0, v37, s[52:53]
	v_or_b32_e32 v31, v31, v43
	v_xor_b32_e32 v43, v27, v43
	v_cndmask_b32_e64 v27, v43, v37, s[50:51]
.Lbs_u27:
	s_andn2_b64 s[48:49], exec, s[44:45]
	s_cbranch_scc0 .Lbs_end
	v_and_b32_e32 v32, v24, v169
	v_bcnt_u32_b32 v38, v32, v41
	s_cmp_lt_i32 s41, 16
	s_cbranch_scc1 .Lbs_c26
	v_and_b32_e32 v33, v25, v218
	v_bcnt_u32_b32 v38, v33, v38
	s_cmp_lt_i32 s41, 32
	s_cbranch_scc1 .Lbs_c26
	v_and_b32_e32 v36, v26, v246
	v_bcnt_u32_b32 v38, v36, v38
	s_cmp_lt_i32 s41, 48
	s_cbranch_scc1 .Lbs_c26
	v_and_b32_e32 v37, v27, v9
	v_bcnt_u32_b32 v38, v37, v38
.Lbs_c26:
	v_mov_b32_e32 v39, v38
	v_mov_b32_e32 v40, v38
	s_nop 1
	v_permlane32_swap_b32_e32 v39, v40
	v_add_u32_e32 v39, v39, v40
	v_cmp_ne_u32_e32 vcc, 0, v39
	s_and_b64 vcc, vcc, s[58:59]
	s_and_saveexec_b64 s[54:55], vcc
	ds_add_u32 v136, v39 offset:640
	s_mov_b64 exec, s[54:55]
	s_waitcnt lgkmcnt(0)
	s_barrier
	ds_read_b32 v42, v136 offset:640
	s_waitcnt lgkmcnt(0)
	v_cmp_lt_u32_e64 s[48:49], s42, v42
	v_cmp_eq_u32_e32 vcc, s43, v42
	s_andn2_b64 s[50:51], s[48:49], s[44:45]
	s_or_b64 s[48:49], s[48:49], s[44:45]
	s_andn2_b64 s[52:53], exec, s[48:49]
	s_or_b64 s[46:47], s[46:47], s[50:51]
	s_or_b64 s[44:45], s[44:45], vcc
	v_cndmask_b32_e64 v41, v41, v38, s[52:53]
	v_cndmask_b32_e64 v43, 0, v32, s[52:53]
	v_or_b32_e32 v28, v28, v43
	v_xor_b32_e32 v43, v24, v43
	v_cndmask_b32_e64 v24, v43, v32, s[50:51]
	s_cmp_lt_i32 s41, 16
	s_cbranch_scc1 .Lbs_u26
	v_cndmask_b32_e64 v43, 0, v33, s[52:53]
	v_or_b32_e32 v29, v29, v43
	v_xor_b32_e32 v43, v25, v43
	v_cndmask_b32_e64 v25, v43, v33, s[50:51]
	s_cmp_lt_i32 s41, 32
	s_cbranch_scc1 .Lbs_u26
	v_cndmask_b32_e64 v43, 0, v36, s[52:53]
	v_or_b32_e32 v30, v30, v43
	v_xor_b32_e32 v43, v26, v43
	v_cndmask_b32_e64 v26, v43, v36, s[50:51]
	s_cmp_lt_i32 s41, 48
	s_cbranch_scc1 .Lbs_u26
	v_cndmask_b32_e64 v43, 0, v37, s[52:53]
	v_or_b32_e32 v31, v31, v43
	v_xor_b32_e32 v43, v27, v43
	v_cndmask_b32_e64 v27, v43, v37, s[50:51]
.Lbs_u26:
	s_andn2_b64 s[48:49], exec, s[44:45]
	s_cbranch_scc0 .Lbs_end
	v_and_b32_e32 v32, v24, v164
	v_bcnt_u32_b32 v38, v32, v41
	s_cmp_lt_i32 s41, 16
	s_cbranch_scc1 .Lbs_c25
	v_and_b32_e32 v33, v25, v215
	v_bcnt_u32_b32 v38, v33, v38
	s_cmp_lt_i32 s41, 32
	s_cbranch_scc1 .Lbs_c25
	v_and_b32_e32 v36, v26, v231
	v_bcnt_u32_b32 v38, v36, v38
	s_cmp_lt_i32 s41, 48
	s_cbranch_scc1 .Lbs_c25
	v_and_b32_e32 v37, v27, v10
	v_bcnt_u32_b32 v38, v37, v38
; DI void a1_task(unsigned char* shm, const bf16_t* prm, const bf16_t* prt, unsigned* mask, int b, int qt, const int tid) {
;     ...
;             const unsigned cand = T | (1u << bit);
;             int c = 0;
; #pragma unroll
;             for (int jt = 0; jt < 8; ++jt) {
;                 if (jt < nheld) {
; #pragma unroll
;                     for (int i = 0; i < 16; ++i) c += (key[jt][i] >= cand) ? 1 : 0;
;                 }
;             }
;             c += __shfl_xor(c, 32);
;             if (h == 0 && c) atomicAdd(&cnt[(31 - bit) * 32 + r], (unsigned)c);
;             __syncthreads();
;             const unsigned tot = cnt[(31 - bit) * 32 + r];
;             if (!done) { if (tot >= 256u) T = cand; if (tot == 256u) done = true; }
;             if (__ballot(!done) == 0ull) break;
;         }
.Lbs_c25:
	v_mov_b32_e32 v39, v38
	v_mov_b32_e32 v40, v38
	s_nop 1
	v_permlane32_swap_b32_e32 v39, v40
	v_add_u32_e32 v39, v39, v40
	v_cmp_ne_u32_e32 vcc, 0, v39
	s_and_b64 vcc, vcc, s[58:59]
	s_and_saveexec_b64 s[54:55], vcc
	ds_add_u32 v136, v39 offset:768
	s_mov_b64 exec, s[54:55]
	s_waitcnt lgkmcnt(0)
	s_barrier
	ds_read_b32 v42, v136 offset:768
	s_waitcnt lgkmcnt(0)
	v_cmp_lt_u32_e64 s[48:49], s42, v42
	v_cmp_eq_u32_e32 vcc, s43, v42
	s_andn2_b64 s[50:51], s[48:49], s[44:45]
	s_or_b64 s[48:49], s[48:49], s[44:45]
	s_andn2_b64 s[52:53], exec, s[48:49]
	s_or_b64 s[46:47], s[46:47], s[50:51]
	s_or_b64 s[44:45], s[44:45], vcc
	v_cndmask_b32_e64 v41, v41, v38, s[52:53]
	v_cndmask_b32_e64 v43, 0, v32, s[52:53]
	v_or_b32_e32 v28, v28, v43
	v_xor_b32_e32 v43, v24, v43
	v_cndmask_b32_e64 v24, v43, v32, s[50:51]
	s_cmp_lt_i32 s41, 16
	s_cbranch_scc1 .Lbs_u25
	v_cndmask_b32_e64 v43, 0, v33, s[52:53]
	v_or_b32_e32 v29, v29, v43
	v_xor_b32_e32 v43, v25, v43
	v_cndmask_b32_e64 v25, v43, v33, s[50:51]
	s_cmp_lt_i32 s41, 32
	s_cbranch_scc1 .Lbs_u25
	v_cndmask_b32_e64 v43, 0, v36, s[52:53]
	v_or_b32_e32 v30, v30, v43
	v_xor_b32_e32 v43, v26, v43
	v_cndmask_b32_e64 v26, v43, v36, s[50:51]
	s_cmp_lt_i32 s41, 48
	s_cbranch_scc1 .Lbs_u25
	v_cndmask_b32_e64 v43, 0, v37, s[52:53]
	v_or_b32_e32 v31, v31, v43
	v_xor_b32_e32 v43, v27, v43
	v_cndmask_b32_e64 v27, v43, v37, s[50:51]
.Lbs_u25:
	s_andn2_b64 s[48:49], exec, s[44:45]
	s_cbranch_scc0 .Lbs_end
	v_and_b32_e32 v32, v24, v165
	v_bcnt_u32_b32 v38, v32, v41
	s_cmp_lt_i32 s41, 16
	s_cbranch_scc1 .Lbs_c24
	v_and_b32_e32 v33, v25, v216
	v_bcnt_u32_b32 v38, v33, v38
	s_cmp_lt_i32 s41, 32
	s_cbranch_scc1 .Lbs_c24
	v_and_b32_e32 v36, v26, v244
	v_bcnt_u32_b32 v38, v36, v38
	s_cmp_lt_i32 s41, 48
	s_cbranch_scc1 .Lbs_c24
	v_and_b32_e32 v37, v27, v11
	v_bcnt_u32_b32 v38, v37, v38
.Lbs_c24:
	v_mov_b32_e32 v39, v38
	v_mov_b32_e32 v40, v38
	s_nop 1
	v_permlane32_swap_b32_e32 v39, v40
	v_add_u32_e32 v39, v39, v40
	v_cmp_ne_u32_e32 vcc, 0, v39
	s_and_b64 vcc, vcc, s[58:59]
	s_and_saveexec_b64 s[54:55], vcc
	ds_add_u32 v136, v39 offset:896
	s_mov_b64 exec, s[54:55]
	s_waitcnt lgkmcnt(0)
	s_barrier
	ds_read_b32 v42, v136 offset:896
	s_waitcnt lgkmcnt(0)
	v_cmp_lt_u32_e64 s[48:49], s42, v42
	v_cmp_eq_u32_e32 vcc, s43, v42
	s_andn2_b64 s[50:51], s[48:49], s[44:45]
	s_or_b64 s[48:49], s[48:49], s[44:45]
	s_andn2_b64 s[52:53], exec, s[48:49]
	s_or_b64 s[46:47], s[46:47], s[50:51]
	s_or_b64 s[44:45], s[44:45], vcc
	v_cndmask_b32_e64 v41, v41, v38, s[52:53]
	v_cndmask_b32_e64 v43, 0, v32, s[52:53]
	v_or_b32_e32 v28, v28, v43
	v_xor_b32_e32 v43, v24, v43
	v_cndmask_b32_e64 v24, v43, v32, s[50:51]
	s_cmp_lt_i32 s41, 16
	s_cbranch_scc1 .Lbs_u24
	v_cndmask_b32_e64 v43, 0, v33, s[52:53]
	v_or_b32_e32 v29, v29, v43
	v_xor_b32_e32 v43, v25, v43
	v_cndmask_b32_e64 v25, v43, v33, s[50:51]
	s_cmp_lt_i32 s41, 32
	s_cbranch_scc1 .Lbs_u24
	v_cndmask_b32_e64 v43, 0, v36, s[52:53]
	v_or_b32_e32 v30, v30, v43
	v_xor_b32_e32 v43, v26, v43
	v_cndmask_b32_e64 v26, v43, v36, s[50:51]
	s_cmp_lt_i32 s41, 48
	s_cbranch_scc1 .Lbs_u24
	v_cndmask_b32_e64 v43, 0, v37, s[52:53]
	v_or_b32_e32 v31, v31, v43
	v_xor_b32_e32 v43, v27, v43
	v_cndmask_b32_e64 v27, v43, v37, s[50:51]
.Lbs_u24:
	s_andn2_b64 s[48:49], exec, s[44:45]
	s_cbranch_scc0 .Lbs_end
	v_and_b32_e32 v32, v24, v163
	v_bcnt_u32_b32 v38, v32, v41
	s_cmp_lt_i32 s41, 16
	s_cbranch_scc1 .Lbs_c23
	v_and_b32_e32 v33, v25, v214
	v_bcnt_u32_b32 v38, v33, v38
	s_cmp_lt_i32 s41, 32
	s_cbranch_scc1 .Lbs_c23
	v_and_b32_e32 v36, v26, v97
	v_bcnt_u32_b32 v38, v36, v38
	s_cmp_lt_i32 s41, 48
	s_cbranch_scc1 .Lbs_c23
	v_and_b32_e32 v37, v27, v13
	v_bcnt_u32_b32 v38, v37, v38
.Lbs_c23:
	v_mov_b32_e32 v39, v38
	v_mov_b32_e32 v40, v38
	s_nop 1
	v_permlane32_swap_b32_e32 v39, v40
	v_add_u32_e32 v39, v39, v40
	v_cmp_ne_u32_e32 vcc, 0, v39
	s_and_b64 vcc, vcc, s[58:59]
	s_and_saveexec_b64 s[54:55], vcc
	ds_add_u32 v136, v39 offset:1024
	s_mov_b64 exec, s[54:55]
	s_waitcnt lgkmcnt(0)
	s_barrier
	ds_read_b32 v42, v136 offset:1024
	s_waitcnt lgkmcnt(0)
	v_cmp_lt_u32_e64 s[48:49], s42, v42
	v_cmp_eq_u32_e32 vcc, s43, v42
	s_andn2_b64 s[50:51], s[48:49], s[44:45]
	s_or_b64 s[48:49], s[48:49], s[44:45]
	s_andn2_b64 s[52:53], exec, s[48:49]
	s_or_b64 s[46:47], s[46:47], s[50:51]
	s_or_b64 s[44:45], s[44:45], vcc
	v_cndmask_b32_e64 v41, v41, v38, s[52:53]
	v_cndmask_b32_e64 v43, 0, v32, s[52:53]
	v_or_b32_e32 v28, v28, v43
	v_xor_b32_e32 v43, v24, v43
	v_cndmask_b32_e64 v24, v43, v32, s[50:51]
	s_cmp_lt_i32 s41, 16
	s_cbranch_scc1 .Lbs_u23
	v_cndmask_b32_e64 v43, 0, v33, s[52:53]
	v_or_b32_e32 v29, v29, v43
	v_xor_b32_e32 v43, v25, v43
	v_cndmask_b32_e64 v25, v43, v33, s[50:51]
	s_cmp_lt_i32 s41, 32
	s_cbranch_scc1 .Lbs_u23
	v_cndmask_b32_e64 v43, 0, v36, s[52:53]
	v_or_b32_e32 v30, v30, v43
	v_xor_b32_e32 v43, v26, v43
	v_cndmask_b32_e64 v26, v43, v36, s[50:51]
	s_cmp_lt_i32 s41, 48
	s_cbranch_scc1 .Lbs_u23
	v_cndmask_b32_e64 v43, 0, v37, s[52:53]
	v_or_b32_e32 v31, v31, v43
	v_xor_b32_e32 v43, v27, v43
	v_cndmask_b32_e64 v27, v43, v37, s[50:51]
.Lbs_u23:
	s_andn2_b64 s[48:49], exec, s[44:45]
	s_cbranch_scc0 .Lbs_end
	v_and_b32_e32 v32, v24, v160
	v_bcnt_u32_b32 v38, v32, v41
	s_cmp_lt_i32 s41, 16
	s_cbranch_scc1 .Lbs_c22
	v_and_b32_e32 v33, v25, v211
	v_bcnt_u32_b32 v38, v33, v38
	s_cmp_lt_i32 s41, 32
	s_cbranch_scc1 .Lbs_c22
	v_and_b32_e32 v36, v26, v94
	v_bcnt_u32_b32 v38, v36, v38
	s_cmp_lt_i32 s41, 48
	s_cbranch_scc1 .Lbs_c22
	v_and_b32_e32 v37, v27, v14
	v_bcnt_u32_b32 v38, v37, v38
; DI void a1_task(unsigned char* shm, const bf16_t* prm, const bf16_t* prt, unsigned* mask, int b, int qt, const int tid) {
;     ...
;             const unsigned cand = T | (1u << bit);
;             int c = 0;
; #pragma unroll
;             for (int jt = 0; jt < 8; ++jt) {
;                 if (jt < nheld) {
; #pragma unroll
;                     for (int i = 0; i < 16; ++i) c += (key[jt][i] >= cand) ? 1 : 0;
;                 }
;             }
;             c += __shfl_xor(c, 32);
;             if (h == 0 && c) atomicAdd(&cnt[(31 - bit) * 32 + r], (unsigned)c);
;             __syncthreads();
;             const unsigned tot = cnt[(31 - bit) * 32 + r];
;             if (!done) { if (tot >= 256u) T = cand; if (tot == 256u) done = true; }
;             if (__ballot(!done) == 0ull) break;
;         }
.Lbs_c22:
	v_mov_b32_e32 v39, v38
	v_mov_b32_e32 v40, v38
	s_nop 1
	v_permlane32_swap_b32_e32 v39, v40
	v_add_u32_e32 v39, v39, v40
	v_cmp_ne_u32_e32 vcc, 0, v39
	s_and_b64 vcc, vcc, s[58:59]
	s_and_saveexec_b64 s[54:55], vcc
	ds_add_u32 v136, v39 offset:1152
	s_mov_b64 exec, s[54:55]
	s_waitcnt lgkmcnt(0)
	s_barrier
	ds_read_b32 v42, v136 offset:1152
	s_waitcnt lgkmcnt(0)
	v_cmp_lt_u32_e64 s[48:49], s42, v42
	v_cmp_eq_u32_e32 vcc, s43, v42
	s_andn2_b64 s[50:51], s[48:49], s[44:45]
	s_or_b64 s[48:49], s[48:49], s[44:45]
	s_andn2_b64 s[52:53], exec, s[48:49]
	s_or_b64 s[46:47], s[46:47], s[50:51]
	s_or_b64 s[44:45], s[44:45], vcc
	v_cndmask_b32_e64 v41, v41, v38, s[52:53]
	v_cndmask_b32_e64 v43, 0, v32, s[52:53]
	v_or_b32_e32 v28, v28, v43
	v_xor_b32_e32 v43, v24, v43
	v_cndmask_b32_e64 v24, v43, v32, s[50:51]
	s_cmp_lt_i32 s41, 16
	s_cbranch_scc1 .Lbs_u22
	v_cndmask_b32_e64 v43, 0, v33, s[52:53]
	v_or_b32_e32 v29, v29, v43
	v_xor_b32_e32 v43, v25, v43
	v_cndmask_b32_e64 v25, v43, v33, s[50:51]
	s_cmp_lt_i32 s41, 32
	s_cbranch_scc1 .Lbs_u22
	v_cndmask_b32_e64 v43, 0, v36, s[52:53]
	v_or_b32_e32 v30, v30, v43
	v_xor_b32_e32 v43, v26, v43
	v_cndmask_b32_e64 v26, v43, v36, s[50:51]
	s_cmp_lt_i32 s41, 48
	s_cbranch_scc1 .Lbs_u22
	v_cndmask_b32_e64 v43, 0, v37, s[52:53]
	v_or_b32_e32 v31, v31, v43
	v_xor_b32_e32 v43, v27, v43
	v_cndmask_b32_e64 v27, v43, v37, s[50:51]
.Lbs_u22:
	s_andn2_b64 s[48:49], exec, s[44:45]
	s_cbranch_scc0 .Lbs_end
	v_and_b32_e32 v32, v24, v161
	v_bcnt_u32_b32 v38, v32, v41
	s_cmp_lt_i32 s41, 16
	s_cbranch_scc1 .Lbs_c21
	v_and_b32_e32 v33, v25, v212
	v_bcnt_u32_b32 v38, v33, v38
	s_cmp_lt_i32 s41, 32
	s_cbranch_scc1 .Lbs_c21
	v_and_b32_e32 v36, v26, v95
	v_bcnt_u32_b32 v38, v36, v38
	s_cmp_lt_i32 s41, 48
	s_cbranch_scc1 .Lbs_c21
	v_and_b32_e32 v37, v27, v15
	v_bcnt_u32_b32 v38, v37, v38
.Lbs_c21:
	v_mov_b32_e32 v39, v38
	v_mov_b32_e32 v40, v38
	s_nop 1
	v_permlane32_swap_b32_e32 v39, v40
	v_add_u32_e32 v39, v39, v40
	v_cmp_ne_u32_e32 vcc, 0, v39
	s_and_b64 vcc, vcc, s[58:59]
	s_and_saveexec_b64 s[54:55], vcc
	ds_add_u32 v136, v39 offset:1280
	s_mov_b64 exec, s[54:55]
	s_waitcnt lgkmcnt(0)
	s_barrier
	ds_read_b32 v42, v136 offset:1280
	s_waitcnt lgkmcnt(0)
	v_cmp_lt_u32_e64 s[48:49], s42, v42
	v_cmp_eq_u32_e32 vcc, s43, v42
	s_andn2_b64 s[50:51], s[48:49], s[44:45]
	s_or_b64 s[48:49], s[48:49], s[44:45]
	s_andn2_b64 s[52:53], exec, s[48:49]
	s_or_b64 s[46:47], s[46:47], s[50:51]
	s_or_b64 s[44:45], s[44:45], vcc
	v_cndmask_b32_e64 v41, v41, v38, s[52:53]
	v_cndmask_b32_e64 v43, 0, v32, s[52:53]
	v_or_b32_e32 v28, v28, v43
	v_xor_b32_e32 v43, v24, v43
	v_cndmask_b32_e64 v24, v43, v32, s[50:51]
	s_cmp_lt_i32 s41, 16
	s_cbranch_scc1 .Lbs_u21
	v_cndmask_b32_e64 v43, 0, v33, s[52:53]
	v_or_b32_e32 v29, v29, v43
	v_xor_b32_e32 v43, v25, v43
	v_cndmask_b32_e64 v25, v43, v33, s[50:51]
	s_cmp_lt_i32 s41, 32
	s_cbranch_scc1 .Lbs_u21
	v_cndmask_b32_e64 v43, 0, v36, s[52:53]
	v_or_b32_e32 v30, v30, v43
	v_xor_b32_e32 v43, v26, v43
	v_cndmask_b32_e64 v26, v43, v36, s[50:51]
	s_cmp_lt_i32 s41, 48
	s_cbranch_scc1 .Lbs_u21
	v_cndmask_b32_e64 v43, 0, v37, s[52:53]
	v_or_b32_e32 v31, v31, v43
	v_xor_b32_e32 v43, v27, v43
	v_cndmask_b32_e64 v27, v43, v37, s[50:51]
.Lbs_u21:
	s_andn2_b64 s[48:49], exec, s[44:45]
	s_cbranch_scc0 .Lbs_end
	v_and_b32_e32 v32, v24, v158
	v_bcnt_u32_b32 v38, v32, v41
	s_cmp_lt_i32 s41, 16
	s_cbranch_scc1 .Lbs_c20
	v_and_b32_e32 v33, v25, v192
	v_bcnt_u32_b32 v38, v33, v38
	s_cmp_lt_i32 s41, 32
	s_cbranch_scc1 .Lbs_c20
	v_and_b32_e32 v36, v26, v88
	v_bcnt_u32_b32 v38, v36, v38
	s_cmp_lt_i32 s41, 48
	s_cbranch_scc1 .Lbs_c20
	v_and_b32_e32 v37, v27, v16
	v_bcnt_u32_b32 v38, v37, v38
.Lbs_c20:
	v_mov_b32_e32 v39, v38
	v_mov_b32_e32 v40, v38
	s_nop 1
	v_permlane32_swap_b32_e32 v39, v40
	v_add_u32_e32 v39, v39, v40
	v_cmp_ne_u32_e32 vcc, 0, v39
	s_and_b64 vcc, vcc, s[58:59]
	s_and_saveexec_b64 s[54:55], vcc
	ds_add_u32 v136, v39 offset:1408
	s_mov_b64 exec, s[54:55]
	s_waitcnt lgkmcnt(0)
	s_barrier
	ds_read_b32 v42, v136 offset:1408
	s_waitcnt lgkmcnt(0)
	v_cmp_lt_u32_e64 s[48:49], s42, v42
	v_cmp_eq_u32_e32 vcc, s43, v42
	s_andn2_b64 s[50:51], s[48:49], s[44:45]
	s_or_b64 s[48:49], s[48:49], s[44:45]
	s_andn2_b64 s[52:53], exec, s[48:49]
	s_or_b64 s[46:47], s[46:47], s[50:51]
	s_or_b64 s[44:45], s[44:45], vcc
	v_cndmask_b32_e64 v41, v41, v38, s[52:53]
	v_cndmask_b32_e64 v43, 0, v32, s[52:53]
	v_or_b32_e32 v28, v28, v43
	v_xor_b32_e32 v43, v24, v43
	v_cndmask_b32_e64 v24, v43, v32, s[50:51]
	s_cmp_lt_i32 s41, 16
	s_cbranch_scc1 .Lbs_u20
	v_cndmask_b32_e64 v43, 0, v33, s[52:53]
	v_or_b32_e32 v29, v29, v43
	v_xor_b32_e32 v43, v25, v43
	v_cndmask_b32_e64 v25, v43, v33, s[50:51]
	s_cmp_lt_i32 s41, 32
	s_cbranch_scc1 .Lbs_u20
	v_cndmask_b32_e64 v43, 0, v36, s[52:53]
	v_or_b32_e32 v30, v30, v43
	v_xor_b32_e32 v43, v26, v43
	v_cndmask_b32_e64 v26, v43, v36, s[50:51]
	s_cmp_lt_i32 s41, 48
	s_cbranch_scc1 .Lbs_u20
	v_cndmask_b32_e64 v43, 0, v37, s[52:53]
	v_or_b32_e32 v31, v31, v43
	v_xor_b32_e32 v43, v27, v43
	v_cndmask_b32_e64 v27, v43, v37, s[50:51]
.Lbs_u20:
	s_andn2_b64 s[48:49], exec, s[44:45]
	s_cbranch_scc0 .Lbs_end
	v_and_b32_e32 v32, v24, v159
	v_bcnt_u32_b32 v38, v32, v41
	s_cmp_lt_i32 s41, 16
	s_cbranch_scc1 .Lbs_c19
	v_and_b32_e32 v33, v25, v193
	v_bcnt_u32_b32 v38, v33, v38
	s_cmp_lt_i32 s41, 32
	s_cbranch_scc1 .Lbs_c19
	v_and_b32_e32 v36, v26, v89
	v_bcnt_u32_b32 v38, v36, v38
	s_cmp_lt_i32 s41, 48
	s_cbranch_scc1 .Lbs_c19
	v_and_b32_e32 v37, v27, v17
	v_bcnt_u32_b32 v38, v37, v38
; DI void a1_task(unsigned char* shm, const bf16_t* prm, const bf16_t* prt, unsigned* mask, int b, int qt, const int tid) {
;     ...
;             const unsigned cand = T | (1u << bit);
;             int c = 0;
; #pragma unroll
;             for (int jt = 0; jt < 8; ++jt) {
;                 if (jt < nheld) {
; #pragma unroll
;                     for (int i = 0; i < 16; ++i) c += (key[jt][i] >= cand) ? 1 : 0;
;                 }
;             }
;             c += __shfl_xor(c, 32);
;             if (h == 0 && c) atomicAdd(&cnt[(31 - bit) * 32 + r], (unsigned)c);
;             __syncthreads();
;             const unsigned tot = cnt[(31 - bit) * 32 + r];
;             if (!done) { if (tot >= 256u) T = cand; if (tot == 256u) done = true; }
;             if (__ballot(!done) == 0ull) break;
;         }
.Lbs_c19:
	v_mov_b32_e32 v39, v38
	v_mov_b32_e32 v40, v38
	s_nop 1
	v_permlane32_swap_b32_e32 v39, v40
	v_add_u32_e32 v39, v39, v40
	v_cmp_ne_u32_e32 vcc, 0, v39
	s_and_b64 vcc, vcc, s[58:59]
	s_and_saveexec_b64 s[54:55], vcc
	ds_add_u32 v136, v39 offset:1536
	s_mov_b64 exec, s[54:55]
	s_waitcnt lgkmcnt(0)
	s_barrier
	ds_read_b32 v42, v136 offset:1536
	s_waitcnt lgkmcnt(0)
	v_cmp_lt_u32_e64 s[48:49], s42, v42
	v_cmp_eq_u32_e32 vcc, s43, v42
	s_andn2_b64 s[50:51], s[48:49], s[44:45]
	s_or_b64 s[48:49], s[48:49], s[44:45]
	s_andn2_b64 s[52:53], exec, s[48:49]
	s_or_b64 s[46:47], s[46:47], s[50:51]
	s_or_b64 s[44:45], s[44:45], vcc
	v_cndmask_b32_e64 v41, v41, v38, s[52:53]
	v_cndmask_b32_e64 v43, 0, v32, s[52:53]
	v_or_b32_e32 v28, v28, v43
	v_xor_b32_e32 v43, v24, v43
	v_cndmask_b32_e64 v24, v43, v32, s[50:51]
	s_cmp_lt_i32 s41, 16
	s_cbranch_scc1 .Lbs_u19
	v_cndmask_b32_e64 v43, 0, v33, s[52:53]
	v_or_b32_e32 v29, v29, v43
	v_xor_b32_e32 v43, v25, v43
	v_cndmask_b32_e64 v25, v43, v33, s[50:51]
	s_cmp_lt_i32 s41, 32
	s_cbranch_scc1 .Lbs_u19
	v_cndmask_b32_e64 v43, 0, v36, s[52:53]
	v_or_b32_e32 v30, v30, v43
	v_xor_b32_e32 v43, v26, v43
	v_cndmask_b32_e64 v26, v43, v36, s[50:51]
	s_cmp_lt_i32 s41, 48
	s_cbranch_scc1 .Lbs_u19
	v_cndmask_b32_e64 v43, 0, v37, s[52:53]
	v_or_b32_e32 v31, v31, v43
	v_xor_b32_e32 v43, v27, v43
	v_cndmask_b32_e64 v27, v43, v37, s[50:51]
.Lbs_u19:
	s_andn2_b64 s[48:49], exec, s[44:45]
	s_cbranch_scc0 .Lbs_end
	v_and_b32_e32 v32, v24, v167
	v_bcnt_u32_b32 v38, v32, v41
	s_cmp_lt_i32 s41, 16
	s_cbranch_scc1 .Lbs_c18
	v_and_b32_e32 v33, v25, v190
	v_bcnt_u32_b32 v38, v33, v38
	s_cmp_lt_i32 s41, 32
	s_cbranch_scc1 .Lbs_c18
	v_and_b32_e32 v36, v26, v86
	v_bcnt_u32_b32 v38, v36, v38
	s_cmp_lt_i32 s41, 48
	s_cbranch_scc1 .Lbs_c18
	v_and_b32_e32 v37, v27, v34
	v_bcnt_u32_b32 v38, v37, v38
.Lbs_c18:
	v_mov_b32_e32 v39, v38
	v_mov_b32_e32 v40, v38
	s_nop 1
	v_permlane32_swap_b32_e32 v39, v40
	v_add_u32_e32 v39, v39, v40
	v_cmp_ne_u32_e32 vcc, 0, v39
	s_and_b64 vcc, vcc, s[58:59]
	s_and_saveexec_b64 s[54:55], vcc
	ds_add_u32 v136, v39 offset:1664
	s_mov_b64 exec, s[54:55]
	s_waitcnt lgkmcnt(0)
	s_barrier
	ds_read_b32 v42, v136 offset:1664
	s_waitcnt lgkmcnt(0)
	v_cmp_lt_u32_e64 s[48:49], s42, v42
	v_cmp_eq_u32_e32 vcc, s43, v42
	s_andn2_b64 s[50:51], s[48:49], s[44:45]
	s_or_b64 s[48:49], s[48:49], s[44:45]
	s_andn2_b64 s[52:53], exec, s[48:49]
	s_or_b64 s[46:47], s[46:47], s[50:51]
	s_or_b64 s[44:45], s[44:45], vcc
	v_cndmask_b32_e64 v41, v41, v38, s[52:53]
	v_cndmask_b32_e64 v43, 0, v32, s[52:53]
	v_or_b32_e32 v28, v28, v43
	v_xor_b32_e32 v43, v24, v43
	v_cndmask_b32_e64 v24, v43, v32, s[50:51]
	s_cmp_lt_i32 s41, 16
	s_cbranch_scc1 .Lbs_u18
	v_cndmask_b32_e64 v43, 0, v33, s[52:53]
	v_or_b32_e32 v29, v29, v43
	v_xor_b32_e32 v43, v25, v43
	v_cndmask_b32_e64 v25, v43, v33, s[50:51]
	s_cmp_lt_i32 s41, 32
	s_cbranch_scc1 .Lbs_u18
	v_cndmask_b32_e64 v43, 0, v36, s[52:53]
	v_or_b32_e32 v30, v30, v43
	v_xor_b32_e32 v43, v26, v43
	v_cndmask_b32_e64 v26, v43, v36, s[50:51]
	s_cmp_lt_i32 s41, 48
	s_cbranch_scc1 .Lbs_u18
	v_cndmask_b32_e64 v43, 0, v37, s[52:53]
	v_or_b32_e32 v31, v31, v43
	v_xor_b32_e32 v43, v27, v43
	v_cndmask_b32_e64 v27, v43, v37, s[50:51]
.Lbs_u18:
	s_andn2_b64 s[48:49], exec, s[44:45]
	s_cbranch_scc0 .Lbs_end
	v_and_b32_e32 v32, v24, v166
	v_bcnt_u32_b32 v38, v32, v41
	s_cmp_lt_i32 s41, 16
	s_cbranch_scc1 .Lbs_c17
	v_and_b32_e32 v33, v25, v191
	v_bcnt_u32_b32 v38, v33, v38
	s_cmp_lt_i32 s41, 32
	s_cbranch_scc1 .Lbs_c17
	v_and_b32_e32 v36, v26, v87
	v_bcnt_u32_b32 v38, v36, v38
	s_cmp_lt_i32 s41, 48
	s_cbranch_scc1 .Lbs_c17
	v_and_b32_e32 v37, v27, v35
	v_bcnt_u32_b32 v38, v37, v38
.Lbs_c17:
	v_mov_b32_e32 v39, v38
	v_mov_b32_e32 v40, v38
	s_nop 1
	v_permlane32_swap_b32_e32 v39, v40
	v_add_u32_e32 v39, v39, v40
	v_cmp_ne_u32_e32 vcc, 0, v39
	s_and_b64 vcc, vcc, s[58:59]
	s_and_saveexec_b64 s[54:55], vcc
	ds_add_u32 v136, v39 offset:1792
	s_mov_b64 exec, s[54:55]
	s_waitcnt lgkmcnt(0)
	s_barrier
	ds_read_b32 v42, v136 offset:1792
	s_waitcnt lgkmcnt(0)
	v_cmp_lt_u32_e64 s[48:49], s42, v42
	v_cmp_eq_u32_e32 vcc, s43, v42
	s_andn2_b64 s[50:51], s[48:49], s[44:45]
	s_or_b64 s[48:49], s[48:49], s[44:45]
	s_andn2_b64 s[52:53], exec, s[48:49]
	s_or_b64 s[46:47], s[46:47], s[50:51]
	s_or_b64 s[44:45], s[44:45], vcc
	v_cndmask_b32_e64 v41, v41, v38, s[52:53]
	v_cndmask_b32_e64 v43, 0, v32, s[52:53]
	v_or_b32_e32 v28, v28, v43
	v_xor_b32_e32 v43, v24, v43
	v_cndmask_b32_e64 v24, v43, v32, s[50:51]
	s_cmp_lt_i32 s41, 16
	s_cbranch_scc1 .Lbs_u17
	v_cndmask_b32_e64 v43, 0, v33, s[52:53]
	v_or_b32_e32 v29, v29, v43
	v_xor_b32_e32 v43, v25, v43
	v_cndmask_b32_e64 v25, v43, v33, s[50:51]
	s_cmp_lt_i32 s41, 32
	s_cbranch_scc1 .Lbs_u17
	v_cndmask_b32_e64 v43, 0, v36, s[52:53]
	v_or_b32_e32 v30, v30, v43
	v_xor_b32_e32 v43, v26, v43
	v_cndmask_b32_e64 v26, v43, v36, s[50:51]
	s_cmp_lt_i32 s41, 48
	s_cbranch_scc1 .Lbs_u17
	v_cndmask_b32_e64 v43, 0, v37, s[52:53]
	v_or_b32_e32 v31, v31, v43
	v_xor_b32_e32 v43, v27, v43
	v_cndmask_b32_e64 v27, v43, v37, s[50:51]
.Lbs_u17:
	s_andn2_b64 s[48:49], exec, s[44:45]
	s_cbranch_scc0 .Lbs_end
	v_and_b32_e32 v32, v24, v149
	v_bcnt_u32_b32 v38, v32, v41
	s_cmp_lt_i32 s41, 16
	s_cbranch_scc1 .Lbs_c16
	v_and_b32_e32 v33, v25, v181
	v_bcnt_u32_b32 v38, v33, v38
	s_cmp_lt_i32 s41, 32
	s_cbranch_scc1 .Lbs_c16
	v_and_b32_e32 v36, v26, v93
	v_bcnt_u32_b32 v38, v36, v38
	s_cmp_lt_i32 s41, 48
	s_cbranch_scc1 .Lbs_c16
	v_and_b32_e32 v37, v27, v57
	v_bcnt_u32_b32 v38, v37, v38
; DI void a1_task(unsigned char* shm, const bf16_t* prm, const bf16_t* prt, unsigned* mask, int b, int qt, const int tid) {
;     ...
;             const unsigned cand = T | (1u << bit);
;             int c = 0;
; #pragma unroll
;             for (int jt = 0; jt < 8; ++jt) {
;                 if (jt < nheld) {
; #pragma unroll
;                     for (int i = 0; i < 16; ++i) c += (key[jt][i] >= cand) ? 1 : 0;
;                 }
;             }
;             c += __shfl_xor(c, 32);
;             if (h == 0 && c) atomicAdd(&cnt[(31 - bit) * 32 + r], (unsigned)c);
;             __syncthreads();
;             const unsigned tot = cnt[(31 - bit) * 32 + r];
;             if (!done) { if (tot >= 256u) T = cand; if (tot == 256u) done = true; }
;             if (__ballot(!done) == 0ull) break;
;         }
.Lbs_c16:
	v_mov_b32_e32 v39, v38
	v_mov_b32_e32 v40, v38
	s_nop 1
	v_permlane32_swap_b32_e32 v39, v40
	v_add_u32_e32 v39, v39, v40
	v_cmp_ne_u32_e32 vcc, 0, v39
	s_and_b64 vcc, vcc, s[58:59]
	s_and_saveexec_b64 s[54:55], vcc
	ds_add_u32 v136, v39 offset:1920
	s_mov_b64 exec, s[54:55]
	s_waitcnt lgkmcnt(0)
	s_barrier
	ds_read_b32 v42, v136 offset:1920
	s_waitcnt lgkmcnt(0)
	v_cmp_lt_u32_e64 s[48:49], s42, v42
	v_cmp_eq_u32_e32 vcc, s43, v42
	s_andn2_b64 s[50:51], s[48:49], s[44:45]
	s_or_b64 s[48:49], s[48:49], s[44:45]
	s_andn2_b64 s[52:53], exec, s[48:49]
	s_or_b64 s[46:47], s[46:47], s[50:51]
	s_or_b64 s[44:45], s[44:45], vcc
	v_cndmask_b32_e64 v41, v41, v38, s[52:53]
	v_cndmask_b32_e64 v43, 0, v32, s[52:53]
	v_or_b32_e32 v28, v28, v43
	v_xor_b32_e32 v43, v24, v43
	v_cndmask_b32_e64 v24, v43, v32, s[50:51]
	s_cmp_lt_i32 s41, 16
	s_cbranch_scc1 .Lbs_u16
	v_cndmask_b32_e64 v43, 0, v33, s[52:53]
	v_or_b32_e32 v29, v29, v43
	v_xor_b32_e32 v43, v25, v43
	v_cndmask_b32_e64 v25, v43, v33, s[50:51]
	s_cmp_lt_i32 s41, 32
	s_cbranch_scc1 .Lbs_u16
	v_cndmask_b32_e64 v43, 0, v36, s[52:53]
	v_or_b32_e32 v30, v30, v43
	v_xor_b32_e32 v43, v26, v43
	v_cndmask_b32_e64 v26, v43, v36, s[50:51]
	s_cmp_lt_i32 s41, 48
	s_cbranch_scc1 .Lbs_u16
	v_cndmask_b32_e64 v43, 0, v37, s[52:53]
	v_or_b32_e32 v31, v31, v43
	v_xor_b32_e32 v43, v27, v43
	v_cndmask_b32_e64 v27, v43, v37, s[50:51]
.Lbs_u16:
	s_andn2_b64 s[48:49], exec, s[44:45]
	s_cbranch_scc0 .Lbs_end
	v_and_b32_e32 v32, v24, v157
	v_bcnt_u32_b32 v38, v32, v41
	s_cmp_lt_i32 s41, 16
	s_cbranch_scc1 .Lbs_c15
	v_and_b32_e32 v33, v25, v189
	v_bcnt_u32_b32 v38, v33, v38
	s_cmp_lt_i32 s41, 32
	s_cbranch_scc1 .Lbs_c15
	v_and_b32_e32 v36, v26, v230
	v_bcnt_u32_b32 v38, v36, v38
	s_cmp_lt_i32 s41, 48
	s_cbranch_scc1 .Lbs_c15
	v_and_b32_e32 v37, v27, v65
	v_bcnt_u32_b32 v38, v37, v38
.Lbs_c15:
	v_mov_b32_e32 v39, v38
	v_mov_b32_e32 v40, v38
	s_nop 1
	v_permlane32_swap_b32_e32 v39, v40
	v_add_u32_e32 v39, v39, v40
	v_cmp_ne_u32_e32 vcc, 0, v39
	s_and_b64 vcc, vcc, s[58:59]
	s_and_saveexec_b64 s[54:55], vcc
	ds_add_u32 v136, v39 offset:2048
	s_mov_b64 exec, s[54:55]
	s_waitcnt lgkmcnt(0)
	s_barrier
	ds_read_b32 v42, v136 offset:2048
	s_waitcnt lgkmcnt(0)
	v_cmp_lt_u32_e64 s[48:49], s42, v42
	v_cmp_eq_u32_e32 vcc, s43, v42
	s_andn2_b64 s[50:51], s[48:49], s[44:45]
	s_or_b64 s[48:49], s[48:49], s[44:45]
	s_andn2_b64 s[52:53], exec, s[48:49]
	s_or_b64 s[46:47], s[46:47], s[50:51]
	s_or_b64 s[44:45], s[44:45], vcc
	v_cndmask_b32_e64 v41, v41, v38, s[52:53]
	v_cndmask_b32_e64 v43, 0, v32, s[52:53]
	v_or_b32_e32 v28, v28, v43
	v_xor_b32_e32 v43, v24, v43
	v_cndmask_b32_e64 v24, v43, v32, s[50:51]
	s_cmp_lt_i32 s41, 16
	s_cbranch_scc1 .Lbs_u15
	v_cndmask_b32_e64 v43, 0, v33, s[52:53]
	v_or_b32_e32 v29, v29, v43
	v_xor_b32_e32 v43, v25, v43
	v_cndmask_b32_e64 v25, v43, v33, s[50:51]
	s_cmp_lt_i32 s41, 32
	s_cbranch_scc1 .Lbs_u15
	v_cndmask_b32_e64 v43, 0, v36, s[52:53]
	v_or_b32_e32 v30, v30, v43
	v_xor_b32_e32 v43, v26, v43
	v_cndmask_b32_e64 v26, v43, v36, s[50:51]
	s_cmp_lt_i32 s41, 48
	s_cbranch_scc1 .Lbs_u15
	v_cndmask_b32_e64 v43, 0, v37, s[52:53]
	v_or_b32_e32 v31, v31, v43
	v_xor_b32_e32 v43, v27, v43
	v_cndmask_b32_e64 v27, v43, v37, s[50:51]
.Lbs_u15:
	s_andn2_b64 s[48:49], exec, s[44:45]
	s_cbranch_scc0 .Lbs_end
	v_and_b32_e32 v32, v24, v154
	v_bcnt_u32_b32 v38, v32, v41
	s_cmp_lt_i32 s41, 16
	s_cbranch_scc1 .Lbs_c14
	v_and_b32_e32 v33, v25, v186
	v_bcnt_u32_b32 v38, v33, v38
	s_cmp_lt_i32 s41, 32
	s_cbranch_scc1 .Lbs_c14
	v_and_b32_e32 v36, v26, v227
	v_bcnt_u32_b32 v38, v36, v38
	s_cmp_lt_i32 s41, 48
	s_cbranch_scc1 .Lbs_c14
	v_and_b32_e32 v37, v27, v62
	v_bcnt_u32_b32 v38, v37, v38
.Lbs_c14:
	v_mov_b32_e32 v39, v38
	v_mov_b32_e32 v40, v38
	s_nop 1
	v_permlane32_swap_b32_e32 v39, v40
	v_add_u32_e32 v39, v39, v40
	v_cmp_ne_u32_e32 vcc, 0, v39
	s_and_b64 vcc, vcc, s[58:59]
	s_and_saveexec_b64 s[54:55], vcc
	ds_add_u32 v136, v39 offset:2176
	s_mov_b64 exec, s[54:55]
	s_waitcnt lgkmcnt(0)
	s_barrier
	ds_read_b32 v42, v136 offset:2176
	s_waitcnt lgkmcnt(0)
	v_cmp_lt_u32_e64 s[48:49], s42, v42
	v_cmp_eq_u32_e32 vcc, s43, v42
	s_andn2_b64 s[50:51], s[48:49], s[44:45]
	s_or_b64 s[48:49], s[48:49], s[44:45]
	s_andn2_b64 s[52:53], exec, s[48:49]
	s_or_b64 s[46:47], s[46:47], s[50:51]
	s_or_b64 s[44:45], s[44:45], vcc
	v_cndmask_b32_e64 v41, v41, v38, s[52:53]
	v_cndmask_b32_e64 v43, 0, v32, s[52:53]
	v_or_b32_e32 v28, v28, v43
	v_xor_b32_e32 v43, v24, v43
	v_cndmask_b32_e64 v24, v43, v32, s[50:51]
	s_cmp_lt_i32 s41, 16
	s_cbranch_scc1 .Lbs_u14
	v_cndmask_b32_e64 v43, 0, v33, s[52:53]
	v_or_b32_e32 v29, v29, v43
	v_xor_b32_e32 v43, v25, v43
	v_cndmask_b32_e64 v25, v43, v33, s[50:51]
	s_cmp_lt_i32 s41, 32
	s_cbranch_scc1 .Lbs_u14
	v_cndmask_b32_e64 v43, 0, v36, s[52:53]
	v_or_b32_e32 v30, v30, v43
	v_xor_b32_e32 v43, v26, v43
	v_cndmask_b32_e64 v26, v43, v36, s[50:51]
	s_cmp_lt_i32 s41, 48
	s_cbranch_scc1 .Lbs_u14
	v_cndmask_b32_e64 v43, 0, v37, s[52:53]
	v_or_b32_e32 v31, v31, v43
	v_xor_b32_e32 v43, v27, v43
	v_cndmask_b32_e64 v27, v43, v37, s[50:51]
.Lbs_u14:
	s_andn2_b64 s[48:49], exec, s[44:45]
	s_cbranch_scc0 .Lbs_end
	v_and_b32_e32 v32, v24, v155
	v_bcnt_u32_b32 v38, v32, v41
	s_cmp_lt_i32 s41, 16
	s_cbranch_scc1 .Lbs_c13
	v_and_b32_e32 v33, v25, v187
	v_bcnt_u32_b32 v38, v33, v38
	s_cmp_lt_i32 s41, 32
	s_cbranch_scc1 .Lbs_c13
	v_and_b32_e32 v36, v26, v228
	v_bcnt_u32_b32 v38, v36, v38
	s_cmp_lt_i32 s41, 48
	s_cbranch_scc1 .Lbs_c13
	v_and_b32_e32 v37, v27, v63
	v_bcnt_u32_b32 v38, v37, v38
; DI void a1_task(unsigned char* shm, const bf16_t* prm, const bf16_t* prt, unsigned* mask, int b, int qt, const int tid) {
;     ...
;             const unsigned cand = T | (1u << bit);
;             int c = 0;
; #pragma unroll
;             for (int jt = 0; jt < 8; ++jt) {
;                 if (jt < nheld) {
; #pragma unroll
;                     for (int i = 0; i < 16; ++i) c += (key[jt][i] >= cand) ? 1 : 0;
;                 }
;             }
;             c += __shfl_xor(c, 32);
;             if (h == 0 && c) atomicAdd(&cnt[(31 - bit) * 32 + r], (unsigned)c);
;             __syncthreads();
;             const unsigned tot = cnt[(31 - bit) * 32 + r];
;             if (!done) { if (tot >= 256u) T = cand; if (tot == 256u) done = true; }
;             if (__ballot(!done) == 0ull) break;
;         }
.Lbs_c13:
	v_mov_b32_e32 v39, v38
	v_mov_b32_e32 v40, v38
	s_nop 1
	v_permlane32_swap_b32_e32 v39, v40
	v_add_u32_e32 v39, v39, v40
	v_cmp_ne_u32_e32 vcc, 0, v39
	s_and_b64 vcc, vcc, s[58:59]
	s_and_saveexec_b64 s[54:55], vcc
	ds_add_u32 v136, v39 offset:2304
	s_mov_b64 exec, s[54:55]
	s_waitcnt lgkmcnt(0)
	s_barrier
	ds_read_b32 v42, v136 offset:2304
	s_waitcnt lgkmcnt(0)
	v_cmp_lt_u32_e64 s[48:49], s42, v42
	v_cmp_eq_u32_e32 vcc, s43, v42
	s_andn2_b64 s[50:51], s[48:49], s[44:45]
	s_or_b64 s[48:49], s[48:49], s[44:45]
	s_andn2_b64 s[52:53], exec, s[48:49]
	s_or_b64 s[46:47], s[46:47], s[50:51]
	s_or_b64 s[44:45], s[44:45], vcc
	v_cndmask_b32_e64 v41, v41, v38, s[52:53]
	v_cndmask_b32_e64 v43, 0, v32, s[52:53]
	v_or_b32_e32 v28, v28, v43
	v_xor_b32_e32 v43, v24, v43
	v_cndmask_b32_e64 v24, v43, v32, s[50:51]
	s_cmp_lt_i32 s41, 16
	s_cbranch_scc1 .Lbs_u13
	v_cndmask_b32_e64 v43, 0, v33, s[52:53]
	v_or_b32_e32 v29, v29, v43
	v_xor_b32_e32 v43, v25, v43
	v_cndmask_b32_e64 v25, v43, v33, s[50:51]
	s_cmp_lt_i32 s41, 32
	s_cbranch_scc1 .Lbs_u13
	v_cndmask_b32_e64 v43, 0, v36, s[52:53]
	v_or_b32_e32 v30, v30, v43
	v_xor_b32_e32 v43, v26, v43
	v_cndmask_b32_e64 v26, v43, v36, s[50:51]
	s_cmp_lt_i32 s41, 48
	s_cbranch_scc1 .Lbs_u13
	v_cndmask_b32_e64 v43, 0, v37, s[52:53]
	v_or_b32_e32 v31, v31, v43
	v_xor_b32_e32 v43, v27, v43
	v_cndmask_b32_e64 v27, v43, v37, s[50:51]
.Lbs_u13:
	s_andn2_b64 s[48:49], exec, s[44:45]
	s_cbranch_scc0 .Lbs_end
	v_and_b32_e32 v32, v24, v152
	v_bcnt_u32_b32 v38, v32, v41
	s_cmp_lt_i32 s41, 16
	s_cbranch_scc1 .Lbs_c12
	v_and_b32_e32 v33, v25, v184
	v_bcnt_u32_b32 v38, v33, v38
	s_cmp_lt_i32 s41, 32
	s_cbranch_scc1 .Lbs_c12
	v_and_b32_e32 v36, v26, v225
	v_bcnt_u32_b32 v38, v36, v38
	s_cmp_lt_i32 s41, 48
	s_cbranch_scc1 .Lbs_c12
	v_and_b32_e32 v37, v27, v60
	v_bcnt_u32_b32 v38, v37, v38
.Lbs_c12:
	v_mov_b32_e32 v39, v38
	v_mov_b32_e32 v40, v38
	s_nop 1
	v_permlane32_swap_b32_e32 v39, v40
	v_add_u32_e32 v39, v39, v40
	v_cmp_ne_u32_e32 vcc, 0, v39
	s_and_b64 vcc, vcc, s[58:59]
	s_and_saveexec_b64 s[54:55], vcc
	ds_add_u32 v136, v39 offset:2432
	s_mov_b64 exec, s[54:55]
	s_waitcnt lgkmcnt(0)
	s_barrier
	ds_read_b32 v42, v136 offset:2432
	s_waitcnt lgkmcnt(0)
	v_cmp_lt_u32_e64 s[48:49], s42, v42
	v_cmp_eq_u32_e32 vcc, s43, v42
	s_andn2_b64 s[50:51], s[48:49], s[44:45]
	s_or_b64 s[48:49], s[48:49], s[44:45]
	s_andn2_b64 s[52:53], exec, s[48:49]
	s_or_b64 s[46:47], s[46:47], s[50:51]
	s_or_b64 s[44:45], s[44:45], vcc
	v_cndmask_b32_e64 v41, v41, v38, s[52:53]
	v_cndmask_b32_e64 v43, 0, v32, s[52:53]
	v_or_b32_e32 v28, v28, v43
	v_xor_b32_e32 v43, v24, v43
	v_cndmask_b32_e64 v24, v43, v32, s[50:51]
	s_cmp_lt_i32 s41, 16
	s_cbranch_scc1 .Lbs_u12
	v_cndmask_b32_e64 v43, 0, v33, s[52:53]
	v_or_b32_e32 v29, v29, v43
	v_xor_b32_e32 v43, v25, v43
	v_cndmask_b32_e64 v25, v43, v33, s[50:51]
	s_cmp_lt_i32 s41, 32
	s_cbranch_scc1 .Lbs_u12
	v_cndmask_b32_e64 v43, 0, v36, s[52:53]
	v_or_b32_e32 v30, v30, v43
	v_xor_b32_e32 v43, v26, v43
	v_cndmask_b32_e64 v26, v43, v36, s[50:51]
	s_cmp_lt_i32 s41, 48
	s_cbranch_scc1 .Lbs_u12
	v_cndmask_b32_e64 v43, 0, v37, s[52:53]
	v_or_b32_e32 v31, v31, v43
	v_xor_b32_e32 v43, v27, v43
	v_cndmask_b32_e64 v27, v43, v37, s[50:51]
.Lbs_u12:
	s_andn2_b64 s[48:49], exec, s[44:45]
	s_cbranch_scc0 .Lbs_end
	v_and_b32_e32 v32, v24, v153
	v_bcnt_u32_b32 v38, v32, v41
	s_cmp_lt_i32 s41, 16
	s_cbranch_scc1 .Lbs_c11
	v_and_b32_e32 v33, v25, v185
	v_bcnt_u32_b32 v38, v33, v38
	s_cmp_lt_i32 s41, 32
	s_cbranch_scc1 .Lbs_c11
	v_and_b32_e32 v36, v26, v226
	v_bcnt_u32_b32 v38, v36, v38
	s_cmp_lt_i32 s41, 48
	s_cbranch_scc1 .Lbs_c11
	v_and_b32_e32 v37, v27, v61
	v_bcnt_u32_b32 v38, v37, v38
.Lbs_c11:
	v_mov_b32_e32 v39, v38
	v_mov_b32_e32 v40, v38
	s_nop 1
	v_permlane32_swap_b32_e32 v39, v40
	v_add_u32_e32 v39, v39, v40
	v_cmp_ne_u32_e32 vcc, 0, v39
	s_and_b64 vcc, vcc, s[58:59]
	s_and_saveexec_b64 s[54:55], vcc
	ds_add_u32 v136, v39 offset:2560
	s_mov_b64 exec, s[54:55]
	s_waitcnt lgkmcnt(0)
	s_barrier
	ds_read_b32 v42, v136 offset:2560
	s_waitcnt lgkmcnt(0)
	v_cmp_lt_u32_e64 s[48:49], s42, v42
	v_cmp_eq_u32_e32 vcc, s43, v42
	s_andn2_b64 s[50:51], s[48:49], s[44:45]
	s_or_b64 s[48:49], s[48:49], s[44:45]
	s_andn2_b64 s[52:53], exec, s[48:49]
	s_or_b64 s[46:47], s[46:47], s[50:51]
	s_or_b64 s[44:45], s[44:45], vcc
	v_cndmask_b32_e64 v41, v41, v38, s[52:53]
	v_cndmask_b32_e64 v43, 0, v32, s[52:53]
	v_or_b32_e32 v28, v28, v43
	v_xor_b32_e32 v43, v24, v43
	v_cndmask_b32_e64 v24, v43, v32, s[50:51]
	s_cmp_lt_i32 s41, 16
	s_cbranch_scc1 .Lbs_u11
	v_cndmask_b32_e64 v43, 0, v33, s[52:53]
	v_or_b32_e32 v29, v29, v43
	v_xor_b32_e32 v43, v25, v43
	v_cndmask_b32_e64 v25, v43, v33, s[50:51]
	s_cmp_lt_i32 s41, 32
	s_cbranch_scc1 .Lbs_u11
	v_cndmask_b32_e64 v43, 0, v36, s[52:53]
	v_or_b32_e32 v30, v30, v43
	v_xor_b32_e32 v43, v26, v43
	v_cndmask_b32_e64 v26, v43, v36, s[50:51]
	s_cmp_lt_i32 s41, 48
	s_cbranch_scc1 .Lbs_u11
	v_cndmask_b32_e64 v43, 0, v37, s[52:53]
	v_or_b32_e32 v31, v31, v43
	v_xor_b32_e32 v43, v27, v43
	v_cndmask_b32_e64 v27, v43, v37, s[50:51]
.Lbs_u11:
	s_andn2_b64 s[48:49], exec, s[44:45]
	s_cbranch_scc0 .Lbs_end
	v_and_b32_e32 v32, v24, v150
	v_bcnt_u32_b32 v38, v32, v41
	s_cmp_lt_i32 s41, 16
	s_cbranch_scc1 .Lbs_c10
	v_and_b32_e32 v33, v25, v182
	v_bcnt_u32_b32 v38, v33, v38
	s_cmp_lt_i32 s41, 32
	s_cbranch_scc1 .Lbs_c10
	v_and_b32_e32 v36, v26, v223
	v_bcnt_u32_b32 v38, v36, v38
	s_cmp_lt_i32 s41, 48
	s_cbranch_scc1 .Lbs_c10
	v_and_b32_e32 v37, v27, v58
	v_bcnt_u32_b32 v38, v37, v38
; DI void a1_task(unsigned char* shm, const bf16_t* prm, const bf16_t* prt, unsigned* mask, int b, int qt, const int tid) {
;     ...
;             const unsigned cand = T | (1u << bit);
;             int c = 0;
; #pragma unroll
;             for (int jt = 0; jt < 8; ++jt) {
;                 if (jt < nheld) {
; #pragma unroll
;                     for (int i = 0; i < 16; ++i) c += (key[jt][i] >= cand) ? 1 : 0;
;                 }
;             }
;             c += __shfl_xor(c, 32);
;             if (h == 0 && c) atomicAdd(&cnt[(31 - bit) * 32 + r], (unsigned)c);
;             __syncthreads();
;             const unsigned tot = cnt[(31 - bit) * 32 + r];
;             if (!done) { if (tot >= 256u) T = cand; if (tot == 256u) done = true; }
;             if (__ballot(!done) == 0ull) break;
;         }
.Lbs_c10:
	v_mov_b32_e32 v39, v38
	v_mov_b32_e32 v40, v38
	s_nop 1
	v_permlane32_swap_b32_e32 v39, v40
	v_add_u32_e32 v39, v39, v40
	v_cmp_ne_u32_e32 vcc, 0, v39
	s_and_b64 vcc, vcc, s[58:59]
	s_and_saveexec_b64 s[54:55], vcc
	ds_add_u32 v136, v39 offset:2688
	s_mov_b64 exec, s[54:55]
	s_waitcnt lgkmcnt(0)
	s_barrier
	ds_read_b32 v42, v136 offset:2688
	s_waitcnt lgkmcnt(0)
	v_cmp_lt_u32_e64 s[48:49], s42, v42
	v_cmp_eq_u32_e32 vcc, s43, v42
	s_andn2_b64 s[50:51], s[48:49], s[44:45]
	s_or_b64 s[48:49], s[48:49], s[44:45]
	s_andn2_b64 s[52:53], exec, s[48:49]
	s_or_b64 s[46:47], s[46:47], s[50:51]
	s_or_b64 s[44:45], s[44:45], vcc
	v_cndmask_b32_e64 v41, v41, v38, s[52:53]
	v_cndmask_b32_e64 v43, 0, v32, s[52:53]
	v_or_b32_e32 v28, v28, v43
	v_xor_b32_e32 v43, v24, v43
	v_cndmask_b32_e64 v24, v43, v32, s[50:51]
	s_cmp_lt_i32 s41, 16
	s_cbranch_scc1 .Lbs_u10
	v_cndmask_b32_e64 v43, 0, v33, s[52:53]
	v_or_b32_e32 v29, v29, v43
	v_xor_b32_e32 v43, v25, v43
	v_cndmask_b32_e64 v25, v43, v33, s[50:51]
	s_cmp_lt_i32 s41, 32
	s_cbranch_scc1 .Lbs_u10
	v_cndmask_b32_e64 v43, 0, v36, s[52:53]
	v_or_b32_e32 v30, v30, v43
	v_xor_b32_e32 v43, v26, v43
	v_cndmask_b32_e64 v26, v43, v36, s[50:51]
	s_cmp_lt_i32 s41, 48
	s_cbranch_scc1 .Lbs_u10
	v_cndmask_b32_e64 v43, 0, v37, s[52:53]
	v_or_b32_e32 v31, v31, v43
	v_xor_b32_e32 v43, v27, v43
	v_cndmask_b32_e64 v27, v43, v37, s[50:51]
.Lbs_u10:
	s_andn2_b64 s[48:49], exec, s[44:45]
	s_cbranch_scc0 .Lbs_end
	v_and_b32_e32 v32, v24, v151
	v_bcnt_u32_b32 v38, v32, v41
	s_cmp_lt_i32 s41, 16
	s_cbranch_scc1 .Lbs_c9
	v_and_b32_e32 v33, v25, v183
	v_bcnt_u32_b32 v38, v33, v38
	s_cmp_lt_i32 s41, 32
	s_cbranch_scc1 .Lbs_c9
	v_and_b32_e32 v36, v26, v224
	v_bcnt_u32_b32 v38, v36, v38
	s_cmp_lt_i32 s41, 48
	s_cbranch_scc1 .Lbs_c9
	v_and_b32_e32 v37, v27, v59
	v_bcnt_u32_b32 v38, v37, v38
.Lbs_c9:
	v_mov_b32_e32 v39, v38
	v_mov_b32_e32 v40, v38
	s_nop 1
	v_permlane32_swap_b32_e32 v39, v40
	v_add_u32_e32 v39, v39, v40
	v_cmp_ne_u32_e32 vcc, 0, v39
	s_and_b64 vcc, vcc, s[58:59]
	s_and_saveexec_b64 s[54:55], vcc
	ds_add_u32 v136, v39 offset:2816
	s_mov_b64 exec, s[54:55]
	s_waitcnt lgkmcnt(0)
	s_barrier
	ds_read_b32 v42, v136 offset:2816
	s_waitcnt lgkmcnt(0)
	v_cmp_lt_u32_e64 s[48:49], s42, v42
	v_cmp_eq_u32_e32 vcc, s43, v42
	s_andn2_b64 s[50:51], s[48:49], s[44:45]
	s_or_b64 s[48:49], s[48:49], s[44:45]
	s_andn2_b64 s[52:53], exec, s[48:49]
	s_or_b64 s[46:47], s[46:47], s[50:51]
	s_or_b64 s[44:45], s[44:45], vcc
	v_cndmask_b32_e64 v41, v41, v38, s[52:53]
	v_cndmask_b32_e64 v43, 0, v32, s[52:53]
	v_or_b32_e32 v28, v28, v43
	v_xor_b32_e32 v43, v24, v43
	v_cndmask_b32_e64 v24, v43, v32, s[50:51]
	s_cmp_lt_i32 s41, 16
	s_cbranch_scc1 .Lbs_u9
	v_cndmask_b32_e64 v43, 0, v33, s[52:53]
	v_or_b32_e32 v29, v29, v43
	v_xor_b32_e32 v43, v25, v43
	v_cndmask_b32_e64 v25, v43, v33, s[50:51]
	s_cmp_lt_i32 s41, 32
	s_cbranch_scc1 .Lbs_u9
	v_cndmask_b32_e64 v43, 0, v36, s[52:53]
	v_or_b32_e32 v30, v30, v43
	v_xor_b32_e32 v43, v26, v43
	v_cndmask_b32_e64 v26, v43, v36, s[50:51]
	s_cmp_lt_i32 s41, 48
	s_cbranch_scc1 .Lbs_u9
	v_cndmask_b32_e64 v43, 0, v37, s[52:53]
	v_or_b32_e32 v31, v31, v43
	v_xor_b32_e32 v43, v27, v43
	v_cndmask_b32_e64 v27, v43, v37, s[50:51]
.Lbs_u9:
	s_andn2_b64 s[48:49], exec, s[44:45]
	s_cbranch_scc0 .Lbs_end
	v_and_b32_e32 v32, v24, v147
	v_bcnt_u32_b32 v38, v32, v41
	s_cmp_lt_i32 s41, 16
	s_cbranch_scc1 .Lbs_c8
	v_and_b32_e32 v33, v25, v180
	v_bcnt_u32_b32 v38, v33, v38
	s_cmp_lt_i32 s41, 32
	s_cbranch_scc1 .Lbs_c8
	v_and_b32_e32 v36, v26, v92
	v_bcnt_u32_b32 v38, v36, v38
	s_cmp_lt_i32 s41, 48
	s_cbranch_scc1 .Lbs_c8
	v_and_b32_e32 v37, v27, v56
	v_bcnt_u32_b32 v38, v37, v38
.Lbs_c8:
	v_mov_b32_e32 v39, v38
	v_mov_b32_e32 v40, v38
	s_nop 1
	v_permlane32_swap_b32_e32 v39, v40
	v_add_u32_e32 v39, v39, v40
	v_cmp_ne_u32_e32 vcc, 0, v39
	s_and_b64 vcc, vcc, s[58:59]
	s_and_saveexec_b64 s[54:55], vcc
	ds_add_u32 v136, v39 offset:2944
	s_mov_b64 exec, s[54:55]
	s_waitcnt lgkmcnt(0)
	s_barrier
	ds_read_b32 v42, v136 offset:2944
	s_waitcnt lgkmcnt(0)
	v_cmp_lt_u32_e64 s[48:49], s42, v42
	v_cmp_eq_u32_e32 vcc, s43, v42
	s_andn2_b64 s[50:51], s[48:49], s[44:45]
	s_or_b64 s[48:49], s[48:49], s[44:45]
	s_andn2_b64 s[52:53], exec, s[48:49]
	s_or_b64 s[46:47], s[46:47], s[50:51]
	s_or_b64 s[44:45], s[44:45], vcc
	v_cndmask_b32_e64 v41, v41, v38, s[52:53]
	v_cndmask_b32_e64 v43, 0, v32, s[52:53]
	v_or_b32_e32 v28, v28, v43
	v_xor_b32_e32 v43, v24, v43
	v_cndmask_b32_e64 v24, v43, v32, s[50:51]
	s_cmp_lt_i32 s41, 16
	s_cbranch_scc1 .Lbs_u8
	v_cndmask_b32_e64 v43, 0, v33, s[52:53]
	v_or_b32_e32 v29, v29, v43
	v_xor_b32_e32 v43, v25, v43
	v_cndmask_b32_e64 v25, v43, v33, s[50:51]
	s_cmp_lt_i32 s41, 32
	s_cbranch_scc1 .Lbs_u8
	v_cndmask_b32_e64 v43, 0, v36, s[52:53]
	v_or_b32_e32 v30, v30, v43
	v_xor_b32_e32 v43, v26, v43
	v_cndmask_b32_e64 v26, v43, v36, s[50:51]
	s_cmp_lt_i32 s41, 48
	s_cbranch_scc1 .Lbs_u8
	v_cndmask_b32_e64 v43, 0, v37, s[52:53]
	v_or_b32_e32 v31, v31, v43
	v_xor_b32_e32 v43, v27, v43
	v_cndmask_b32_e64 v27, v43, v37, s[50:51]
.Lbs_u8:
	s_andn2_b64 s[48:49], exec, s[44:45]
	s_cbranch_scc0 .Lbs_end
	v_and_b32_e32 v32, v24, v145
	v_bcnt_u32_b32 v38, v32, v41
	s_cmp_lt_i32 s41, 16
	s_cbranch_scc1 .Lbs_c7
	v_and_b32_e32 v33, v25, v178
	v_bcnt_u32_b32 v38, v33, v38
	s_cmp_lt_i32 s41, 32
	s_cbranch_scc1 .Lbs_c7
	v_and_b32_e32 v36, v26, v90
	v_bcnt_u32_b32 v38, v36, v38
	s_cmp_lt_i32 s41, 48
	s_cbranch_scc1 .Lbs_c7
	v_and_b32_e32 v37, v27, v54
	v_bcnt_u32_b32 v38, v37, v38
; DI void a1_task(unsigned char* shm, const bf16_t* prm, const bf16_t* prt, unsigned* mask, int b, int qt, const int tid) {
;     ...
;             const unsigned cand = T | (1u << bit);
;             int c = 0;
; #pragma unroll
;             for (int jt = 0; jt < 8; ++jt) {
;                 if (jt < nheld) {
; #pragma unroll
;                     for (int i = 0; i < 16; ++i) c += (key[jt][i] >= cand) ? 1 : 0;
;                 }
;             }
;             c += __shfl_xor(c, 32);
;             if (h == 0 && c) atomicAdd(&cnt[(31 - bit) * 32 + r], (unsigned)c);
;             __syncthreads();
;             const unsigned tot = cnt[(31 - bit) * 32 + r];
;             if (!done) { if (tot >= 256u) T = cand; if (tot == 256u) done = true; }
;             if (__ballot(!done) == 0ull) break;
;         }
.Lbs_c7:
	v_mov_b32_e32 v39, v38
	v_mov_b32_e32 v40, v38
	s_nop 1
	v_permlane32_swap_b32_e32 v39, v40
	v_add_u32_e32 v39, v39, v40
	v_cmp_ne_u32_e32 vcc, 0, v39
	s_and_b64 vcc, vcc, s[58:59]
	s_and_saveexec_b64 s[54:55], vcc
	ds_add_u32 v136, v39 offset:3072
	s_mov_b64 exec, s[54:55]
	s_waitcnt lgkmcnt(0)
	s_barrier
	ds_read_b32 v42, v136 offset:3072
	s_waitcnt lgkmcnt(0)
	v_cmp_lt_u32_e64 s[48:49], s42, v42
	v_cmp_eq_u32_e32 vcc, s43, v42
	s_andn2_b64 s[50:51], s[48:49], s[44:45]
	s_or_b64 s[48:49], s[48:49], s[44:45]
	s_andn2_b64 s[52:53], exec, s[48:49]
	s_or_b64 s[46:47], s[46:47], s[50:51]
	s_or_b64 s[44:45], s[44:45], vcc
	v_cndmask_b32_e64 v41, v41, v38, s[52:53]
	v_cndmask_b32_e64 v43, 0, v32, s[52:53]
	v_or_b32_e32 v28, v28, v43
	v_xor_b32_e32 v43, v24, v43
	v_cndmask_b32_e64 v24, v43, v32, s[50:51]
	s_cmp_lt_i32 s41, 16
	s_cbranch_scc1 .Lbs_u7
	v_cndmask_b32_e64 v43, 0, v33, s[52:53]
	v_or_b32_e32 v29, v29, v43
	v_xor_b32_e32 v43, v25, v43
	v_cndmask_b32_e64 v25, v43, v33, s[50:51]
	s_cmp_lt_i32 s41, 32
	s_cbranch_scc1 .Lbs_u7
	v_cndmask_b32_e64 v43, 0, v36, s[52:53]
	v_or_b32_e32 v30, v30, v43
	v_xor_b32_e32 v43, v26, v43
	v_cndmask_b32_e64 v26, v43, v36, s[50:51]
	s_cmp_lt_i32 s41, 48
	s_cbranch_scc1 .Lbs_u7
	v_cndmask_b32_e64 v43, 0, v37, s[52:53]
	v_or_b32_e32 v31, v31, v43
	v_xor_b32_e32 v43, v27, v43
	v_cndmask_b32_e64 v27, v43, v37, s[50:51]
.Lbs_u7:
	s_andn2_b64 s[48:49], exec, s[44:45]
	s_cbranch_scc0 .Lbs_end
	v_and_b32_e32 v32, v24, v146
	v_bcnt_u32_b32 v38, v32, v41
	s_cmp_lt_i32 s41, 16
	s_cbranch_scc1 .Lbs_c6
	v_and_b32_e32 v33, v25, v179
	v_bcnt_u32_b32 v38, v33, v38
	s_cmp_lt_i32 s41, 32
	s_cbranch_scc1 .Lbs_c6
	v_and_b32_e32 v36, v26, v91
	v_bcnt_u32_b32 v38, v36, v38
	s_cmp_lt_i32 s41, 48
	s_cbranch_scc1 .Lbs_c6
	v_and_b32_e32 v37, v27, v55
	v_bcnt_u32_b32 v38, v37, v38
.Lbs_c6:
	v_mov_b32_e32 v39, v38
	v_mov_b32_e32 v40, v38
	s_nop 1
	v_permlane32_swap_b32_e32 v39, v40
	v_add_u32_e32 v39, v39, v40
	v_cmp_ne_u32_e32 vcc, 0, v39
	s_and_b64 vcc, vcc, s[58:59]
	s_and_saveexec_b64 s[54:55], vcc
	ds_add_u32 v136, v39 offset:3200
	s_mov_b64 exec, s[54:55]
	s_waitcnt lgkmcnt(0)
	s_barrier
	ds_read_b32 v42, v136 offset:3200
	s_waitcnt lgkmcnt(0)
	v_cmp_lt_u32_e64 s[48:49], s42, v42
	v_cmp_eq_u32_e32 vcc, s43, v42
	s_andn2_b64 s[50:51], s[48:49], s[44:45]
	s_or_b64 s[48:49], s[48:49], s[44:45]
	s_andn2_b64 s[52:53], exec, s[48:49]
	s_or_b64 s[46:47], s[46:47], s[50:51]
	s_or_b64 s[44:45], s[44:45], vcc
	v_cndmask_b32_e64 v41, v41, v38, s[52:53]
	v_cndmask_b32_e64 v43, 0, v32, s[52:53]
	v_or_b32_e32 v28, v28, v43
	v_xor_b32_e32 v43, v24, v43
	v_cndmask_b32_e64 v24, v43, v32, s[50:51]
	s_cmp_lt_i32 s41, 16
	s_cbranch_scc1 .Lbs_u6
	v_cndmask_b32_e64 v43, 0, v33, s[52:53]
	v_or_b32_e32 v29, v29, v43
	v_xor_b32_e32 v43, v25, v43
	v_cndmask_b32_e64 v25, v43, v33, s[50:51]
	s_cmp_lt_i32 s41, 32
	s_cbranch_scc1 .Lbs_u6
	v_cndmask_b32_e64 v43, 0, v36, s[52:53]
	v_or_b32_e32 v30, v30, v43
	v_xor_b32_e32 v43, v26, v43
	v_cndmask_b32_e64 v26, v43, v36, s[50:51]
	s_cmp_lt_i32 s41, 48
	s_cbranch_scc1 .Lbs_u6
	v_cndmask_b32_e64 v43, 0, v37, s[52:53]
	v_or_b32_e32 v31, v31, v43
	v_xor_b32_e32 v43, v27, v43
	v_cndmask_b32_e64 v27, v43, v37, s[50:51]
.Lbs_u6:
	s_andn2_b64 s[48:49], exec, s[44:45]
	s_cbranch_scc0 .Lbs_end
	v_and_b32_e32 v32, v24, v143
	v_bcnt_u32_b32 v38, v32, v41
	s_cmp_lt_i32 s41, 16
	s_cbranch_scc1 .Lbs_c5
	v_and_b32_e32 v33, v25, v176
	v_bcnt_u32_b32 v38, v33, v38
	s_cmp_lt_i32 s41, 32
	s_cbranch_scc1 .Lbs_c5
	v_and_b32_e32 v36, v26, v84
	v_bcnt_u32_b32 v38, v36, v38
	s_cmp_lt_i32 s41, 48
	s_cbranch_scc1 .Lbs_c5
	v_and_b32_e32 v37, v27, v52
	v_bcnt_u32_b32 v38, v37, v38
.Lbs_c5:
	v_mov_b32_e32 v39, v38
	v_mov_b32_e32 v40, v38
	s_nop 1
	v_permlane32_swap_b32_e32 v39, v40
	v_add_u32_e32 v39, v39, v40
	v_cmp_ne_u32_e32 vcc, 0, v39
	s_and_b64 vcc, vcc, s[58:59]
	s_and_saveexec_b64 s[54:55], vcc
	ds_add_u32 v136, v39 offset:3328
	s_mov_b64 exec, s[54:55]
	s_waitcnt lgkmcnt(0)
	s_barrier
	ds_read_b32 v42, v136 offset:3328
	s_waitcnt lgkmcnt(0)
	v_cmp_lt_u32_e64 s[48:49], s42, v42
	v_cmp_eq_u32_e32 vcc, s43, v42
	s_andn2_b64 s[50:51], s[48:49], s[44:45]
	s_or_b64 s[48:49], s[48:49], s[44:45]
	s_andn2_b64 s[52:53], exec, s[48:49]
	s_or_b64 s[46:47], s[46:47], s[50:51]
	s_or_b64 s[44:45], s[44:45], vcc
	v_cndmask_b32_e64 v41, v41, v38, s[52:53]
	v_cndmask_b32_e64 v43, 0, v32, s[52:53]
	v_or_b32_e32 v28, v28, v43
	v_xor_b32_e32 v43, v24, v43
	v_cndmask_b32_e64 v24, v43, v32, s[50:51]
	s_cmp_lt_i32 s41, 16
	s_cbranch_scc1 .Lbs_u5
	v_cndmask_b32_e64 v43, 0, v33, s[52:53]
	v_or_b32_e32 v29, v29, v43
	v_xor_b32_e32 v43, v25, v43
	v_cndmask_b32_e64 v25, v43, v33, s[50:51]
	s_cmp_lt_i32 s41, 32
	s_cbranch_scc1 .Lbs_u5
	v_cndmask_b32_e64 v43, 0, v36, s[52:53]
	v_or_b32_e32 v30, v30, v43
	v_xor_b32_e32 v43, v26, v43
	v_cndmask_b32_e64 v26, v43, v36, s[50:51]
	s_cmp_lt_i32 s41, 48
	s_cbranch_scc1 .Lbs_u5
	v_cndmask_b32_e64 v43, 0, v37, s[52:53]
	v_or_b32_e32 v31, v31, v43
	v_xor_b32_e32 v43, v27, v43
	v_cndmask_b32_e64 v27, v43, v37, s[50:51]
.Lbs_u5:
	s_andn2_b64 s[48:49], exec, s[44:45]
	s_cbranch_scc0 .Lbs_end
	v_and_b32_e32 v32, v24, v144
	v_bcnt_u32_b32 v38, v32, v41
	s_cmp_lt_i32 s41, 16
	s_cbranch_scc1 .Lbs_c4
	v_and_b32_e32 v33, v25, v177
	v_bcnt_u32_b32 v38, v33, v38
	s_cmp_lt_i32 s41, 32
	s_cbranch_scc1 .Lbs_c4
	v_and_b32_e32 v36, v26, v85
	v_bcnt_u32_b32 v38, v36, v38
	s_cmp_lt_i32 s41, 48
	s_cbranch_scc1 .Lbs_c4
	v_and_b32_e32 v37, v27, v53
	v_bcnt_u32_b32 v38, v37, v38
; DI void a1_task(unsigned char* shm, const bf16_t* prm, const bf16_t* prt, unsigned* mask, int b, int qt, const int tid) {
;     ...
;             const unsigned cand = T | (1u << bit);
;             int c = 0;
; #pragma unroll
;             for (int jt = 0; jt < 8; ++jt) {
;                 if (jt < nheld) {
; #pragma unroll
;                     for (int i = 0; i < 16; ++i) c += (key[jt][i] >= cand) ? 1 : 0;
;                 }
;             }
;             c += __shfl_xor(c, 32);
;             if (h == 0 && c) atomicAdd(&cnt[(31 - bit) * 32 + r], (unsigned)c);
;             __syncthreads();
;             const unsigned tot = cnt[(31 - bit) * 32 + r];
;             if (!done) { if (tot >= 256u) T = cand; if (tot == 256u) done = true; }
;             if (__ballot(!done) == 0ull) break;
;         }
.Lbs_c4:
	v_mov_b32_e32 v39, v38
	v_mov_b32_e32 v40, v38
	s_nop 1
	v_permlane32_swap_b32_e32 v39, v40
	v_add_u32_e32 v39, v39, v40
	v_cmp_ne_u32_e32 vcc, 0, v39
	s_and_b64 vcc, vcc, s[58:59]
	s_and_saveexec_b64 s[54:55], vcc
	ds_add_u32 v136, v39 offset:3456
	s_mov_b64 exec, s[54:55]
	s_waitcnt lgkmcnt(0)
	s_barrier
	ds_read_b32 v42, v136 offset:3456
	s_waitcnt lgkmcnt(0)
	v_cmp_lt_u32_e64 s[48:49], s42, v42
	v_cmp_eq_u32_e32 vcc, s43, v42
	s_andn2_b64 s[50:51], s[48:49], s[44:45]
	s_or_b64 s[48:49], s[48:49], s[44:45]
	s_andn2_b64 s[52:53], exec, s[48:49]
	s_or_b64 s[46:47], s[46:47], s[50:51]
	s_or_b64 s[44:45], s[44:45], vcc
	v_cndmask_b32_e64 v41, v41, v38, s[52:53]
	v_cndmask_b32_e64 v43, 0, v32, s[52:53]
	v_or_b32_e32 v28, v28, v43
	v_xor_b32_e32 v43, v24, v43
	v_cndmask_b32_e64 v24, v43, v32, s[50:51]
	s_cmp_lt_i32 s41, 16
	s_cbranch_scc1 .Lbs_u4
	v_cndmask_b32_e64 v43, 0, v33, s[52:53]
	v_or_b32_e32 v29, v29, v43
	v_xor_b32_e32 v43, v25, v43
	v_cndmask_b32_e64 v25, v43, v33, s[50:51]
	s_cmp_lt_i32 s41, 32
	s_cbranch_scc1 .Lbs_u4
	v_cndmask_b32_e64 v43, 0, v36, s[52:53]
	v_or_b32_e32 v30, v30, v43
	v_xor_b32_e32 v43, v26, v43
	v_cndmask_b32_e64 v26, v43, v36, s[50:51]
	s_cmp_lt_i32 s41, 48
	s_cbranch_scc1 .Lbs_u4
	v_cndmask_b32_e64 v43, 0, v37, s[52:53]
	v_or_b32_e32 v31, v31, v43
	v_xor_b32_e32 v43, v27, v43
	v_cndmask_b32_e64 v27, v43, v37, s[50:51]
.Lbs_u4:
	s_andn2_b64 s[48:49], exec, s[44:45]
	s_cbranch_scc0 .Lbs_end
	v_and_b32_e32 v32, v24, v141
	v_bcnt_u32_b32 v38, v32, v41
	s_cmp_lt_i32 s41, 16
	s_cbranch_scc1 .Lbs_c3
	v_and_b32_e32 v33, v25, v174
	v_bcnt_u32_b32 v38, v33, v38
	s_cmp_lt_i32 s41, 32
	s_cbranch_scc1 .Lbs_c3
	v_and_b32_e32 v36, v26, v82
	v_bcnt_u32_b32 v38, v36, v38
	s_cmp_lt_i32 s41, 48
	s_cbranch_scc1 .Lbs_c3
	v_and_b32_e32 v37, v27, v50
	v_bcnt_u32_b32 v38, v37, v38
.Lbs_c3:
	v_mov_b32_e32 v39, v38
	v_mov_b32_e32 v40, v38
	s_nop 1
	v_permlane32_swap_b32_e32 v39, v40
	v_add_u32_e32 v39, v39, v40
	v_cmp_ne_u32_e32 vcc, 0, v39
	s_and_b64 vcc, vcc, s[58:59]
	s_and_saveexec_b64 s[54:55], vcc
	ds_add_u32 v136, v39 offset:3584
	s_mov_b64 exec, s[54:55]
	s_waitcnt lgkmcnt(0)
	s_barrier
	ds_read_b32 v42, v136 offset:3584
	s_waitcnt lgkmcnt(0)
	v_cmp_lt_u32_e64 s[48:49], s42, v42
	v_cmp_eq_u32_e32 vcc, s43, v42
	s_andn2_b64 s[50:51], s[48:49], s[44:45]
	s_or_b64 s[48:49], s[48:49], s[44:45]
	s_andn2_b64 s[52:53], exec, s[48:49]
	s_or_b64 s[46:47], s[46:47], s[50:51]
	s_or_b64 s[44:45], s[44:45], vcc
	v_cndmask_b32_e64 v41, v41, v38, s[52:53]
	v_cndmask_b32_e64 v43, 0, v32, s[52:53]
	v_or_b32_e32 v28, v28, v43
	v_xor_b32_e32 v43, v24, v43
	v_cndmask_b32_e64 v24, v43, v32, s[50:51]
	s_cmp_lt_i32 s41, 16
	s_cbranch_scc1 .Lbs_u3
	v_cndmask_b32_e64 v43, 0, v33, s[52:53]
	v_or_b32_e32 v29, v29, v43
	v_xor_b32_e32 v43, v25, v43
	v_cndmask_b32_e64 v25, v43, v33, s[50:51]
	s_cmp_lt_i32 s41, 32
	s_cbranch_scc1 .Lbs_u3
	v_cndmask_b32_e64 v43, 0, v36, s[52:53]
	v_or_b32_e32 v30, v30, v43
	v_xor_b32_e32 v43, v26, v43
	v_cndmask_b32_e64 v26, v43, v36, s[50:51]
	s_cmp_lt_i32 s41, 48
	s_cbranch_scc1 .Lbs_u3
	v_cndmask_b32_e64 v43, 0, v37, s[52:53]
	v_or_b32_e32 v31, v31, v43
	v_xor_b32_e32 v43, v27, v43
	v_cndmask_b32_e64 v27, v43, v37, s[50:51]
.Lbs_u3:
	s_andn2_b64 s[48:49], exec, s[44:45]
	s_cbranch_scc0 .Lbs_end
	v_and_b32_e32 v32, v24, v142
	v_bcnt_u32_b32 v38, v32, v41
	s_cmp_lt_i32 s41, 16
	s_cbranch_scc1 .Lbs_c2
	v_and_b32_e32 v33, v25, v175
	v_bcnt_u32_b32 v38, v33, v38
	s_cmp_lt_i32 s41, 32
	s_cbranch_scc1 .Lbs_c2
	v_and_b32_e32 v36, v26, v83
	v_bcnt_u32_b32 v38, v36, v38
	s_cmp_lt_i32 s41, 48
	s_cbranch_scc1 .Lbs_c2
	v_and_b32_e32 v37, v27, v51
	v_bcnt_u32_b32 v38, v37, v38
.Lbs_c2:
	v_mov_b32_e32 v39, v38
	v_mov_b32_e32 v40, v38
	s_nop 1
	v_permlane32_swap_b32_e32 v39, v40
	v_add_u32_e32 v39, v39, v40
	v_cmp_ne_u32_e32 vcc, 0, v39
	s_and_b64 vcc, vcc, s[58:59]
	s_and_saveexec_b64 s[54:55], vcc
	ds_add_u32 v136, v39 offset:3712
	s_mov_b64 exec, s[54:55]
	s_waitcnt lgkmcnt(0)
	s_barrier
	ds_read_b32 v42, v136 offset:3712
	s_waitcnt lgkmcnt(0)
	v_cmp_lt_u32_e64 s[48:49], s42, v42
	v_cmp_eq_u32_e32 vcc, s43, v42
	s_andn2_b64 s[50:51], s[48:49], s[44:45]
	s_or_b64 s[48:49], s[48:49], s[44:45]
	s_andn2_b64 s[52:53], exec, s[48:49]
	s_or_b64 s[46:47], s[46:47], s[50:51]
	s_or_b64 s[44:45], s[44:45], vcc
	v_cndmask_b32_e64 v41, v41, v38, s[52:53]
	v_cndmask_b32_e64 v43, 0, v32, s[52:53]
	v_or_b32_e32 v28, v28, v43
	v_xor_b32_e32 v43, v24, v43
	v_cndmask_b32_e64 v24, v43, v32, s[50:51]
	s_cmp_lt_i32 s41, 16
	s_cbranch_scc1 .Lbs_u2
	v_cndmask_b32_e64 v43, 0, v33, s[52:53]
	v_or_b32_e32 v29, v29, v43
	v_xor_b32_e32 v43, v25, v43
	v_cndmask_b32_e64 v25, v43, v33, s[50:51]
	s_cmp_lt_i32 s41, 32
	s_cbranch_scc1 .Lbs_u2
	v_cndmask_b32_e64 v43, 0, v36, s[52:53]
	v_or_b32_e32 v30, v30, v43
	v_xor_b32_e32 v43, v26, v43
	v_cndmask_b32_e64 v26, v43, v36, s[50:51]
	s_cmp_lt_i32 s41, 48
	s_cbranch_scc1 .Lbs_u2
	v_cndmask_b32_e64 v43, 0, v37, s[52:53]
	v_or_b32_e32 v31, v31, v43
	v_xor_b32_e32 v43, v27, v43
	v_cndmask_b32_e64 v27, v43, v37, s[50:51]
.Lbs_u2:
	s_andn2_b64 s[48:49], exec, s[44:45]
	s_cbranch_scc0 .Lbs_end
	v_and_b32_e32 v32, v24, v18
	v_bcnt_u32_b32 v38, v32, v41
	s_cmp_lt_i32 s41, 16
	s_cbranch_scc1 .Lbs_c1
	v_and_b32_e32 v33, v25, v19
	v_bcnt_u32_b32 v38, v33, v38
	s_cmp_lt_i32 s41, 32
	s_cbranch_scc1 .Lbs_c1
	v_and_b32_e32 v36, v26, v20
	v_bcnt_u32_b32 v38, v36, v38
	s_cmp_lt_i32 s41, 48
	s_cbranch_scc1 .Lbs_c1
	v_and_b32_e32 v37, v27, v21
	v_bcnt_u32_b32 v38, v37, v38
; DI void a1_task(unsigned char* shm, const bf16_t* prm, const bf16_t* prt, unsigned* mask, int b, int qt, const int tid) {
;     ...
;     if (T < 1u) T = 1u;
; #pragma unroll
;     for (int jt = 0; jt < 8; ++jt) {
;         const int kt = wid + 8 * jt;
;         if (kt <= qt) {
;             unsigned part = 0u;
; #pragma unroll
;             for (int i = 0; i < 16; ++i) part |= (key[jt][i] >= T ? 1u : 0u) << (16 * (i >> 3) + 8 * h + (i & 7));
;             part |= (unsigned)__shfl_xor((int)part, 32);
;             if (h == 0) mask[(size_t)(tok0 + t0 + r) * 64 + kt] = part;
;         }
;     }
.Lbs_c1:
	v_mov_b32_e32 v39, v38
	v_mov_b32_e32 v40, v38
	s_nop 1
	v_permlane32_swap_b32_e32 v39, v40
	v_add_u32_e32 v39, v39, v40
	v_cmp_ne_u32_e32 vcc, 0, v39
	s_and_b64 vcc, vcc, s[58:59]
	s_and_saveexec_b64 s[54:55], vcc
	ds_add_u32 v136, v39 offset:3840
	s_mov_b64 exec, s[54:55]
	s_waitcnt lgkmcnt(0)
	s_barrier
	ds_read_b32 v42, v136 offset:3840
	s_waitcnt lgkmcnt(0)
	v_cmp_lt_u32_e64 s[48:49], s42, v42
	v_cmp_eq_u32_e32 vcc, s43, v42
	s_andn2_b64 s[50:51], s[48:49], s[44:45]
	s_or_b64 s[48:49], s[48:49], s[44:45]
	s_andn2_b64 s[52:53], exec, s[48:49]
	s_or_b64 s[46:47], s[46:47], s[50:51]
	s_or_b64 s[44:45], s[44:45], vcc
	v_cndmask_b32_e64 v41, v41, v38, s[52:53]
	v_cndmask_b32_e64 v43, 0, v32, s[52:53]
	v_or_b32_e32 v28, v28, v43
	v_xor_b32_e32 v43, v24, v43
	v_cndmask_b32_e64 v24, v43, v32, s[50:51]
	s_cmp_lt_i32 s41, 16
	s_cbranch_scc1 .Lbs_u1
	v_cndmask_b32_e64 v43, 0, v33, s[52:53]
	v_or_b32_e32 v29, v29, v43
	v_xor_b32_e32 v43, v25, v43
	v_cndmask_b32_e64 v25, v43, v33, s[50:51]
	s_cmp_lt_i32 s41, 32
	s_cbranch_scc1 .Lbs_u1
	v_cndmask_b32_e64 v43, 0, v36, s[52:53]
	v_or_b32_e32 v30, v30, v43
	v_xor_b32_e32 v43, v26, v43
	v_cndmask_b32_e64 v26, v43, v36, s[50:51]
	s_cmp_lt_i32 s41, 48
	s_cbranch_scc1 .Lbs_u1
	v_cndmask_b32_e64 v43, 0, v37, s[52:53]
	v_or_b32_e32 v31, v31, v43
	v_xor_b32_e32 v43, v27, v43
	v_cndmask_b32_e64 v27, v43, v37, s[50:51]
.Lbs_u1:
	s_andn2_b64 s[48:49], exec, s[44:45]
	s_cbranch_scc0 .Lbs_end
	v_and_b32_e32 v32, v24, v156
	v_bcnt_u32_b32 v38, v32, v41
	s_cmp_lt_i32 s41, 16
	s_cbranch_scc1 .Lbs_c0
	v_and_b32_e32 v33, v25, v188
	v_bcnt_u32_b32 v38, v33, v38
	s_cmp_lt_i32 s41, 32
	s_cbranch_scc1 .Lbs_c0
	v_and_b32_e32 v36, v26, v229
	v_bcnt_u32_b32 v38, v36, v38
	s_cmp_lt_i32 s41, 48
	s_cbranch_scc1 .Lbs_c0
	v_and_b32_e32 v37, v27, v64
	v_bcnt_u32_b32 v38, v37, v38
.Lbs_c0:
	v_mov_b32_e32 v39, v38
	v_mov_b32_e32 v40, v38
	s_nop 1
	v_permlane32_swap_b32_e32 v39, v40
	v_add_u32_e32 v39, v39, v40
	v_cmp_ne_u32_e32 vcc, 0, v39
	s_and_b64 vcc, vcc, s[58:59]
	s_and_saveexec_b64 s[54:55], vcc
	ds_add_u32 v136, v39 offset:3968
	s_mov_b64 exec, s[54:55]
	s_waitcnt lgkmcnt(0)
	s_barrier
	ds_read_b32 v42, v136 offset:3968
	s_waitcnt lgkmcnt(0)
	v_cmp_lt_u32_e64 s[48:49], s42, v42
	v_cmp_eq_u32_e32 vcc, s43, v42
	s_andn2_b64 s[50:51], s[48:49], s[44:45]
	s_or_b64 s[48:49], s[48:49], s[44:45]
	s_andn2_b64 s[52:53], exec, s[48:49]
	s_or_b64 s[46:47], s[46:47], s[50:51]
	s_or_b64 s[44:45], s[44:45], vcc
	v_cndmask_b32_e64 v41, v41, v38, s[52:53]
	v_cndmask_b32_e64 v43, 0, v32, s[52:53]
	v_or_b32_e32 v28, v28, v43
	v_xor_b32_e32 v43, v24, v43
	v_cndmask_b32_e64 v24, v43, v32, s[50:51]
	s_cmp_lt_i32 s41, 16
	s_cbranch_scc1 .Lbs_u0
	v_cndmask_b32_e64 v43, 0, v33, s[52:53]
	v_or_b32_e32 v29, v29, v43
	v_xor_b32_e32 v43, v25, v43
	v_cndmask_b32_e64 v25, v43, v33, s[50:51]
	s_cmp_lt_i32 s41, 32
	s_cbranch_scc1 .Lbs_u0
	v_cndmask_b32_e64 v43, 0, v36, s[52:53]
	v_or_b32_e32 v30, v30, v43
	v_xor_b32_e32 v43, v26, v43
	v_cndmask_b32_e64 v26, v43, v36, s[50:51]
	s_cmp_lt_i32 s41, 48
	s_cbranch_scc1 .Lbs_u0
	v_cndmask_b32_e64 v43, 0, v37, s[52:53]
	v_or_b32_e32 v31, v31, v43
	v_xor_b32_e32 v43, v27, v43
	v_cndmask_b32_e64 v27, v43, v37, s[50:51]
.Lbs_u0:
.Lbs_end:
	v_readlane_b32 s0, v255, 37
	s_mov_b32 s42, 0x5010400
	s_mov_b32 s43, 0x7030602
	v_or_b32_e32 v2, s0, v100
	v_ashrrev_i32_e32 v3, 31, v2
	v_readlane_b32 s0, v251, 27
	v_lshlrev_b64 v[2:3], 8, v[2:3]
	v_readlane_b32 s1, v251, 28
	v_readlane_b32 s6, v255, 40
	s_nop 1
	v_lshl_add_u64 v[2:3], s[0:1], 0, v[2:3]
	s_lshl_b32 s6, s6, 2
	s_mov_b32 s7, 0
	v_lshl_add_u64 v[2:3], s[6:7], 0, v[2:3]
	v_cndmask_b32_e64 v43, 0, v24, s[46:47]
	v_or_b32_e32 v43, v28, v43
	v_mov_b32_e32 v39, v43
	s_nop 1
	v_permlane32_swap_b32_e32 v39, v43
	v_perm_b32 v40, v43, v39, s42
	v_perm_b32 v42, v43, v39, s43
	s_mov_b64 exec, s[58:59]
	global_store_dword v[2:3], v40, off
	s_cmp_lt_i32 s41, 8
	s_cbranch_scc1 .Lbs_o0
	global_store_dword v[2:3], v42, off offset:32
.Lbs_o0:
	s_mov_b64 exec, s[8:9]
	s_cmp_lt_i32 s41, 16
	s_cbranch_scc1 .Lbs_out
	v_cndmask_b32_e64 v43, 0, v25, s[46:47]
	v_or_b32_e32 v43, v29, v43
	v_mov_b32_e32 v39, v43
	s_nop 1
	v_permlane32_swap_b32_e32 v39, v43
	v_perm_b32 v40, v43, v39, s42
	v_perm_b32 v42, v43, v39, s43
	s_mov_b64 exec, s[58:59]
	global_store_dword v[2:3], v40, off offset:64
	s_cmp_lt_i32 s41, 24
	s_cbranch_scc1 .Lbs_o1
	global_store_dword v[2:3], v42, off offset:96
.Lbs_o1:
	s_mov_b64 exec, s[8:9]
	s_cmp_lt_i32 s41, 32
	s_cbranch_scc1 .Lbs_out
	v_cndmask_b32_e64 v43, 0, v26, s[46:47]
	v_or_b32_e32 v43, v30, v43
	v_mov_b32_e32 v39, v43
	s_nop 1
	v_permlane32_swap_b32_e32 v39, v43
	v_perm_b32 v40, v43, v39, s42
	v_perm_b32 v42, v43, v39, s43
	s_mov_b64 exec, s[58:59]
	global_store_dword v[2:3], v40, off offset:128
	s_cmp_lt_i32 s41, 40
	s_cbranch_scc1 .Lbs_o2
	global_store_dword v[2:3], v42, off offset:160
.Lbs_o2:
	s_mov_b64 exec, s[8:9]
	s_cmp_lt_i32 s41, 48
	s_cbranch_scc1 .Lbs_out
	v_cndmask_b32_e64 v43, 0, v27, s[46:47]
	v_or_b32_e32 v43, v31, v43
	v_mov_b32_e32 v39, v43
	s_nop 1
	v_permlane32_swap_b32_e32 v39, v43
	v_perm_b32 v40, v43, v39, s42
	v_perm_b32 v42, v43, v39, s43
	s_mov_b64 exec, s[58:59]
	global_store_dword v[2:3], v40, off offset:192
	s_cmp_lt_i32 s41, 56
	s_cbranch_scc1 .Lbs_o3
	global_store_dword v[2:3], v42, off offset:224
.Lbs_o3:
	s_mov_b64 exec, s[8:9]
.Lbs_out:
	s_mov_b64 exec, s[8:9]
	s_branch .LBB0_371
